# LN epilogue row-stat exchange by permlane16/32 swaps (no ds_bpermute); attention loop: fewer VALU (max/add canonicalisation dropped, 64-bit address adds)
# speedup vs baseline: 1.0051x; 1.0051x over previous
; #define SBAR() __builtin_amdgcn_sched_barrier(0)
; #define SLOAD(i, k0) do { sr_[i].vs0 = ld8(&Vh[(long)((k0) + sr) * LDK + sc]); sr_[i].vs1 = ld8(&Vh[(long)((k0) + 32 + sr) * LDK + sc]); \
;     sr_[i].ks0 = ld8(&Kh[(long)((k0) + sr) * LDK + sc]); sr_[i].ks1 = ld8(&Kh[(long)((k0) + 32 + sr) * LDK + sc]); } while (0)
; __device__ __forceinline__ void finishSM(f32x16& p0, f32x16& p1, float alpha, float& l_reg, bf16x8& pa0, bf16x8& pa1, bf16x8& pa2, bf16x8& pa3) {
;   for (int r = 0; r < 16; ++r) p1[r] = __builtin_amdgcn_exp2f(p1[r]);
;   float ps = 0; for (int r = 0; r < 16; ++r) ps += p0[r]; for (int r = 0; r < 16; ++r) ps += p1[r];
;   { auto rr = __builtin_amdgcn_permlane32_swap(__float_as_uint(ps), __float_as_uint(ps), false, false);
;     ps = __uint_as_float(rr[0]) + __uint_as_float(rr[1]); }
;   l_reg = l_reg * alpha + ps;
;     ...
;   PK4(p0, 0, pa0); PK4(p0, 8, pa1); PK4(p1, 0, pa2); PK4(p1, 8, pa3);
;     ...
; }
; __device__ __forceinline__ void attn_body(const bf16_t* Qb, const bf16_t* Kh, const bf16_t* Vh, const bf16_t* Gb, bf16_t* Ob, int seq, char* lds,
;                                           const float* qgain, const float* cosA, const float* sinA, int t0) {
;     ...
;     SBAR(); qkt(pB0, pB1, K_lds + SHM_K, qr, r32, hi);
;     finishSM(pA0, pA1, alA, l_reg, pa0, pa1, pa2, pa3); SBAR();
;     SLOAD(SO, (j + 2) * KVBLK); SBAR();
.LBB0_259:
	ds_read_b128 v[64:67], v201 offset:49152
	ds_read_b128 v[68:71], v201 offset:57344
	ds_read_b128 v[218:221], v204 offset:49152
	ds_read_b128 v[222:225], v204 offset:57344
	ds_read_b128 v[240:243], v205 offset:49152
	ds_read_b128 v[246:249], v205 offset:57344
	v_add_f32_e32 v160, v216, v175
	s_waitcnt lgkmcnt(5)
	v_mfma_f32_32x32x16_bf16 v[80:95], v[64:67], v[100:103], 0
	v_add_f32_e32 v160, v161, v160
	v_add_f32_e32 v160, v213, v160
	v_add_f32_e32 v160, v162, v160
	v_add_f32_e32 v160, v174, v160
	v_add_f32_e32 v160, v163, v160
	v_add_f32_e32 v160, v173, v160
	v_add_f32_e32 v160, v170, v160
	s_waitcnt lgkmcnt(4)
	v_mfma_f32_32x32x16_bf16 v[64:79], v[68:71], v[100:103], 0
	v_add_f32_e32 v160, v172, v160
	v_add_f32_e32 v160, v169, v160
	v_add_f32_e32 v160, v171, v160
	v_exp_f32_e32 v156, v156
	v_add_f32_e32 v160, v166, v160
	v_exp_f32_e32 v157, v157
	v_add_f32_e32 v160, v168, v160
	s_waitcnt lgkmcnt(3)
	v_mfma_f32_32x32x16_bf16 v[80:95], v[218:221], v[108:111], v[80:95]
	v_exp_f32_e32 v154, v154
	v_add_f32_e32 v160, v165, v160
	v_exp_f32_e32 v155, v155
	v_add_f32_e32 v160, v167, v160
	v_exp_f32_e32 v148, v148
	v_add_f32_e32 v160, v156, v160
	v_exp_f32_e32 v149, v149
	s_waitcnt lgkmcnt(2)
	v_mfma_f32_32x32x16_bf16 v[64:79], v[222:225], v[108:111], v[64:79]
	ds_read_b128 v[218:221], v202 offset:49152
	ds_read_b128 v[222:225], v202 offset:57344
	v_add_f32_e32 v160, v157, v160
	v_exp_f32_e32 v146, v146
	v_add_f32_e32 v160, v154, v160
	v_exp_f32_e32 v147, v147
	v_add_f32_e32 v160, v155, v160
	v_exp_f32_e32 v144, v144
	s_waitcnt lgkmcnt(3)
	v_mfma_f32_32x32x16_bf16 v[80:95], v[240:243], v[96:99], v[80:95]
	v_add_f32_e32 v160, v148, v160
	v_exp_f32_e32 v145, v145
	v_add_f32_e32 v160, v149, v160
	v_exp_f32_e32 v158, v158
	v_add_f32_e32 v160, v146, v160
	v_exp_f32_e32 v159, v159
	v_add_f32_e32 v160, v147, v160
	s_waitcnt lgkmcnt(2)
	v_mfma_f32_32x32x16_bf16 v[64:79], v[246:249], v[96:99], v[64:79]
	ds_read_b128 v[240:243], v203 offset:49152
	ds_read_b128 v[246:249], v203 offset:57344
	v_exp_f32_e32 v152, v152
	v_add_f32_e32 v160, v144, v160
	v_exp_f32_e32 v153, v153
	v_add_f32_e32 v160, v145, v160
	v_exp_f32_e32 v150, v150
	v_add_f32_e32 v160, v158, v160
	s_waitcnt lgkmcnt(3)
	v_mfma_f32_32x32x16_bf16 v[80:95], v[218:221], v[104:107], v[80:95]
	v_exp_f32_e32 v151, v151
	v_add_f32_e32 v160, v159, v160
	v_add_f32_e32 v160, v152, v160
	v_add_f32_e32 v160, v153, v160
	v_add_f32_e32 v160, v150, v160
	v_add_f32_e32 v210, v151, v160
	v_mov_b32_e32 v211, v210
	s_waitcnt lgkmcnt(2)
	v_mfma_f32_32x32x16_bf16 v[64:79], v[222:225], v[104:107], v[64:79]
	ds_read_b128 v[218:221], v206 offset:49152
	ds_read_b128 v[222:225], v206 offset:57344
	v_permlane32_swap_b32_e32 v210, v211
	s_waitcnt lgkmcnt(3)
	v_mfma_f32_32x32x16_bf16 v[80:95], v[240:243], v[116:119], v[80:95]
	s_waitcnt lgkmcnt(2)
	v_mfma_f32_32x32x16_bf16 v[64:79], v[246:249], v[116:119], v[64:79]
	ds_read_b128 v[240:243], v207 offset:49152
	ds_read_b128 v[246:249], v207 offset:57344
	s_waitcnt lgkmcnt(3)
	v_mfma_f32_32x32x16_bf16 v[80:95], v[218:221], v[124:127], v[80:95]
	s_waitcnt lgkmcnt(2)
	v_mfma_f32_32x32x16_bf16 v[64:79], v[222:225], v[124:127], v[64:79]
	ds_read_b128 v[218:221], v208 offset:49152
	ds_read_b128 v[222:225], v208 offset:57344
	s_waitcnt lgkmcnt(3)
	v_mfma_f32_32x32x16_bf16 v[80:95], v[240:243], v[112:115], v[80:95]
	s_waitcnt lgkmcnt(2)
	v_mfma_f32_32x32x16_bf16 v[64:79], v[246:249], v[112:115], v[64:79]
	v_cvt_pk_bf16_f32 v160, v175, v216
	v_cvt_pk_bf16_f32 v161, v161, v213
	v_cvt_pk_bf16_f32 v162, v162, v174
	v_cvt_pk_bf16_f32 v163, v163, v173
	v_cvt_pk_bf16_f32 v170, v170, v172
	v_cvt_pk_bf16_f32 v171, v169, v171
	s_waitcnt lgkmcnt(1)
	v_mfma_f32_32x32x16_bf16 v[80:95], v[218:221], v[120:123], v[80:95]
	v_cvt_pk_bf16_f32 v172, v166, v168
	v_cvt_pk_bf16_f32 v173, v165, v167
	v_cvt_pk_bf16_f32 v166, v156, v157
	v_cvt_pk_bf16_f32 v167, v154, v155
	v_cvt_pk_bf16_f32 v168, v148, v149
	v_cvt_pk_bf16_f32 v169, v146, v147
	v_cvt_pk_bf16_f32 v212, v144, v145
	s_waitcnt lgkmcnt(0)
	v_mfma_f32_32x32x16_bf16 v[64:79], v[222:225], v[120:123], v[64:79]
	v_cvt_pk_bf16_f32 v213, v158, v159
	v_cvt_pk_bf16_f32 v214, v152, v153
	v_permlane32_swap_b32_e32 v160, v162
	v_cvt_pk_bf16_f32 v215, v150, v151
	v_permlane32_swap_b32_e32 v212, v214
	v_permlane32_swap_b32_e32 v161, v163
	v_permlane32_swap_b32_e32 v170, v172
	v_permlane32_swap_b32_e32 v171, v173
	v_permlane32_swap_b32_e32 v166, v168
	v_permlane32_swap_b32_e32 v167, v169
	v_permlane32_swap_b32_e32 v213, v215
	s_mov_b32 s20, 0xfff10000
	s_mov_b32 s21, -1
	v_lshl_add_u64 v[148:149], v[182:183], 0, s[20:21]
	s_mov_b32 s20, 0xfff60000
	v_lshl_add_u64 v[152:153], v[182:183], 0, s[20:21]
	s_mov_b32 s20, 0xfffb0000
	v_lshl_add_u64 v[250:251], v[182:183], 0, s[20:21]
	global_load_dwordx4 v[144:147], v[148:149], off
	global_load_dwordx4 v[148:151], v[250:251], off offset:-1024
	global_load_dwordx4 v[156:159], v[152:153], off
	global_load_dwordx4 v[152:155], v[182:183], off offset:-1024
	ds_read_b64_tr_b16 v[216:217], v191 offset:0
	ds_read_b64_tr_b16 v[218:219], v191 offset:0x800
	ds_read_b64_tr_b16 v[220:221], v191 offset:0x1000
	ds_read_b64_tr_b16 v[222:223], v191 offset:0x1800
	ds_read_b64_tr_b16 v[224:225], v191 offset:0x2000
	ds_read_b64_tr_b16 v[226:227], v191 offset:0x2800
	ds_read_b64_tr_b16 v[228:229], v191 offset:0x3000
	ds_read_b64_tr_b16 v[230:231], v191 offset:0x3800
	s_waitcnt lgkmcnt(0)
; #define SWRITE(b, i) do { *(bf16x8*)(V_lds + (b) * SHM_V + vst0) = sr_[i].vs0;          \
;     *(bf16x8*)(V_lds + (b) * SHM_V + vst1) = sr_[i].vs1; int kc = sc * 2;               \
;     *(bf16x8*)(K_lds + (b) * SHM_K + KSWZ(sr, kc)) = sr_[i].ks0;                       \
;     *(bf16x8*)(K_lds + (b) * SHM_K + KSWZ(32 + sr, kc)) = sr_[i].ks1; } while (0)
; #define SWAIT() asm volatile("s_waitcnt vmcnt(4)" ::: "memory")
; #define RESC(a) do { if (__any((a) < 1.f)) { if (hi == 0) al_l[r32] = (a); asm volatile("s_waitcnt lgkmcnt(0)" ::: "memory"); \
;     for (int d = 0; d < 4; ++d) for (int r = 0; r < 16; ++r) o[d][r] *= al_l[crow(r, hi)]; } } while (0)
; __device__ __forceinline__ void partialSM(f32x16& p0, f32x16& p1, float& m_reg, float& mn, float& alpha) {
;   constexpr float C = SCALE * 1.4426950408889634f;
;   float pmax = p0[0]; for (int r = 1; r < 16; ++r) pmax = fmaxf(pmax, p0[r]); for (int r = 0; r < 16; ++r) pmax = fmaxf(pmax, p1[r]);
;   { auto rr = __builtin_amdgcn_permlane32_swap(__float_as_uint(pmax), __float_as_uint(pmax), false, false);
;     pmax = fmaxf(__uint_as_float(rr[0]), __uint_as_float(rr[1])); }
;   if (__builtin_expect(__all(pmax - m_reg <= THR / SCALE), 1)) { mn = m_reg; alpha = 1.f; }
;   else { mn = fmaxf(m_reg, pmax); alpha = __builtin_amdgcn_exp2f((m_reg - mn) * C); m_reg = mn; }
; __device__ __forceinline__ void attn_body(const bf16_t* Qb, const bf16_t* Kh, const bf16_t* Vh, const bf16_t* Gb, bf16_t* Ob, int seq, char* lds,
;                                           const float* qgain, const float* cosA, const float* sinA, int t0) {
;     ...
;     pv_d0(o, vb0, pa0, pa1, pa2, pa3); partialSM(pB0, pB1, m_reg, mnB, alB);
;     __syncthreads(); SWAIT(); SWRITE(0, SE);
;     RESC(alB); __syncthreads();
	s_nop 0
	v_mfma_f32_32x32x16_bf16 v[0:15], v[160:163], v[216:219], v[0:15]
	ds_read_b64_tr_b16 v[216:217], v191 offset:0x200
	ds_read_b64_tr_b16 v[218:219], v191 offset:0xa00
	v_mfma_f32_32x32x16_bf16 v[0:15], v[170:173], v[220:223], v[0:15]
	ds_read_b64_tr_b16 v[220:221], v191 offset:0x1200
	ds_read_b64_tr_b16 v[222:223], v191 offset:0x1a00
	v_mfma_f32_32x32x16_bf16 v[0:15], v[166:169], v[224:227], v[0:15]
	ds_read_b64_tr_b16 v[224:225], v191 offset:0x2200
	ds_read_b64_tr_b16 v[226:227], v191 offset:0x2a00
	v_mfma_f32_32x32x16_bf16 v[0:15], v[212:215], v[228:231], v[0:15]
	ds_read_b64_tr_b16 v[228:229], v191 offset:0x3200
	ds_read_b64_tr_b16 v[230:231], v191 offset:0x3a00
	s_waitcnt lgkmcnt(0)
	v_mfma_f32_32x32x16_bf16 v[48:63], v[160:163], v[216:219], v[48:63]
	ds_read_b64_tr_b16 v[216:217], v191 offset:0x400
	ds_read_b64_tr_b16 v[218:219], v191 offset:0xc00
	v_mfma_f32_32x32x16_bf16 v[48:63], v[170:173], v[220:223], v[48:63]
	ds_read_b64_tr_b16 v[220:221], v191 offset:0x1400
	ds_read_b64_tr_b16 v[222:223], v191 offset:0x1c00
	v_mfma_f32_32x32x16_bf16 v[48:63], v[166:169], v[224:227], v[48:63]
	ds_read_b64_tr_b16 v[224:225], v191 offset:0x2400
	ds_read_b64_tr_b16 v[226:227], v191 offset:0x2c00
	v_mfma_f32_32x32x16_bf16 v[48:63], v[212:215], v[228:231], v[48:63]
	ds_read_b64_tr_b16 v[228:229], v191 offset:0x3400
	ds_read_b64_tr_b16 v[230:231], v191 offset:0x3c00
	s_waitcnt lgkmcnt(0)
	v_mfma_f32_32x32x16_bf16 v[32:47], v[160:163], v[216:219], v[32:47]
	ds_read_b64_tr_b16 v[216:217], v191 offset:0x600
	ds_read_b64_tr_b16 v[218:219], v191 offset:0xe00
	v_mfma_f32_32x32x16_bf16 v[32:47], v[170:173], v[220:223], v[32:47]
	ds_read_b64_tr_b16 v[220:221], v191 offset:0x1600
	ds_read_b64_tr_b16 v[222:223], v191 offset:0x1e00
	v_mfma_f32_32x32x16_bf16 v[32:47], v[166:169], v[224:227], v[32:47]
	ds_read_b64_tr_b16 v[224:225], v191 offset:0x2600
	ds_read_b64_tr_b16 v[226:227], v191 offset:0x2e00
	v_mfma_f32_32x32x16_bf16 v[32:47], v[212:215], v[228:231], v[32:47]
	ds_read_b64_tr_b16 v[228:229], v191 offset:0x3600
	ds_read_b64_tr_b16 v[230:231], v191 offset:0x3e00
	s_waitcnt lgkmcnt(0)
	v_mfma_f32_32x32x16_bf16 v[16:31], v[160:163], v[216:219], v[16:31]
	v_max_f32_e32 v160, v80, v81
	v_max3_f32 v160, v160, v82, v83
	v_max3_f32 v160, v160, v84, v85
	v_max3_f32 v160, v160, v86, v87
	v_max3_f32 v160, v160, v88, v89
	v_max3_f32 v160, v160, v90, v91
	v_max3_f32 v160, v160, v92, v93
	v_mfma_f32_32x32x16_bf16 v[16:31], v[170:173], v[220:223], v[16:31]
	v_max3_f32 v160, v160, v94, v95
	v_max3_f32 v160, v160, v64, v65
	v_max3_f32 v160, v160, v66, v67
	v_max3_f32 v160, v160, v68, v69
	v_max3_f32 v160, v160, v70, v71
	v_max3_f32 v160, v160, v72, v73
	v_max3_f32 v160, v160, v74, v75
	v_max3_f32 v160, v160, v76, v77
	v_mfma_f32_32x32x16_bf16 v[16:31], v[166:169], v[224:227], v[16:31]
	v_max3_f32 v160, v160, v78, v79
	v_mov_b32_e32 v161, v160
	s_nop 1
	v_permlane32_swap_b32_e32 v160, v161
	v_max_f32_e32 v160, v160, v161
	v_sub_f32_e32 v161, v160, v164
	v_cmp_ge_f32_e32 vcc, s71, v161
	v_max_f32_e32 v160, v164, v160
	v_mfma_f32_32x32x16_bf16 v[16:31], v[212:215], v[228:231], v[16:31]
	v_sub_f32_e32 v161, v164, v160
	v_mul_f32_e32 v161, 0x3e0293ee, v161
	v_exp_f32_e32 v161, v161
	s_cmp_eq_u64 vcc, exec
	s_cselect_b64 s[38:39], -1, 0
	s_barrier
	s_waitcnt vmcnt(4)
	v_cndmask_b32_e64 v212, v161, 1.0, s[38:39]
	v_cmp_gt_f32_e32 vcc, 1.0, v212
	s_waitcnt vmcnt(7)
	ds_write_b128 v192, v[128:131]
	s_waitcnt vmcnt(6)
	ds_write_b128 v193, v[132:135]
	s_waitcnt vmcnt(5)
	ds_write_b128 v199, v[136:139] offset:49152
	s_waitcnt vmcnt(4)
	ds_write_b128 v200, v[140:143] offset:49152
	s_cbranch_vccz .LBB0_263
	s_and_saveexec_b64 s[42:43], s[36:37]
	ds_write_b32 v188, v212 offset:128
	s_or_b64 exec, exec, s[42:43]
	s_waitcnt lgkmcnt(0)
	v_add_u32_e32 v161, v187, v176
	ds_read_b128 v[166:169], v161 offset:224
	ds_read_b128 v[170:173], v161 offset:192
	ds_read_b128 v[214:217], v161 offset:160
	ds_read_b128 v[218:221], v161 offset:128
	s_waitcnt lgkmcnt(3)
	v_pk_mul_f32 v[12:13], v[12:13], v[166:167]
	s_waitcnt lgkmcnt(2)
	v_pk_mul_f32 v[8:9], v[8:9], v[170:171]
	s_waitcnt lgkmcnt(1)
	v_pk_mul_f32 v[4:5], v[4:5], v[214:215]
	v_pk_mul_f32 v[14:15], v[14:15], v[168:169]
	v_pk_mul_f32 v[10:11], v[10:11], v[172:173]
	v_pk_mul_f32 v[6:7], v[6:7], v[216:217]
	s_waitcnt lgkmcnt(0)
	v_pk_mul_f32 v[2:3], v[2:3], v[220:221]
	v_pk_mul_f32 v[0:1], v[0:1], v[218:219]
	v_pk_mul_f32 v[60:61], v[60:61], v[166:167]
	v_pk_mul_f32 v[56:57], v[56:57], v[170:171]
	v_pk_mul_f32 v[52:53], v[52:53], v[214:215]
	v_pk_mul_f32 v[62:63], v[62:63], v[168:169]
	v_pk_mul_f32 v[58:59], v[58:59], v[172:173]
	v_pk_mul_f32 v[54:55], v[54:55], v[216:217]
	v_pk_mul_f32 v[50:51], v[50:51], v[220:221]
	v_pk_mul_f32 v[48:49], v[48:49], v[218:219]
	v_pk_mul_f32 v[44:45], v[44:45], v[166:167]
	v_pk_mul_f32 v[40:41], v[40:41], v[170:171]
	v_pk_mul_f32 v[36:37], v[36:37], v[214:215]
	v_pk_mul_f32 v[46:47], v[46:47], v[168:169]
	v_pk_mul_f32 v[42:43], v[42:43], v[172:173]
	v_pk_mul_f32 v[38:39], v[38:39], v[216:217]
	v_pk_mul_f32 v[34:35], v[34:35], v[220:221]
	v_pk_mul_f32 v[32:33], v[32:33], v[218:219]
	v_pk_mul_f32 v[28:29], v[28:29], v[166:167]
	v_pk_mul_f32 v[24:25], v[24:25], v[170:171]
	v_pk_mul_f32 v[20:21], v[20:21], v[214:215]
	v_pk_mul_f32 v[30:31], v[30:31], v[168:169]
	v_pk_mul_f32 v[26:27], v[26:27], v[172:173]
	v_pk_mul_f32 v[22:23], v[22:23], v[216:217]
	v_pk_mul_f32 v[18:19], v[18:19], v[220:221]
	v_pk_mul_f32 v[16:17], v[16:17], v[218:219]
; __device__ __forceinline__ void partialSM(f32x16& p0, f32x16& p1, float& m_reg, float& mn, float& alpha) {
;     ...
;   for (int r = 0; r < 16; ++r) p0[r] = fmaf(p0[r], C, mnC); for (int r = 0; r < 16; ++r) p1[r] = fmaf(p1[r], C, mnC);
;   for (int r = 0; r < 16; ++r) p0[r] = __builtin_amdgcn_exp2f(p0[r]);
; }
; __device__ __forceinline__ void finishSM(f32x16& p0, f32x16& p1, float alpha, float& l_reg, bf16x8& pa0, bf16x8& pa1, bf16x8& pa2, bf16x8& pa3) {
;   for (int r = 0; r < 16; ++r) p1[r] = __builtin_amdgcn_exp2f(p1[r]);
;   float ps = 0; for (int r = 0; r < 16; ++r) ps += p0[r]; for (int r = 0; r < 16; ++r) ps += p1[r];
;   { auto rr = __builtin_amdgcn_permlane32_swap(__float_as_uint(ps), __float_as_uint(ps), false, false);
;     ps = __uint_as_float(rr[0]) + __uint_as_float(rr[1]); }
;   l_reg = l_reg * alpha + ps;
;     ...
;   PK4(p0, 0, pa0); PK4(p0, 8, pa1); PK4(p1, 0, pa2); PK4(p1, 8, pa3);
;     ...
; }
; __device__ __forceinline__ void qkt(f32x16& p0, f32x16& p1, const char* Ks, const bf16x8* qr, int r32, int hi) {
;   p0 = f32x16{}; p1 = f32x16{};
;   for (int d0 = 0; d0 < 8; ++d0) { int cb = (d0 * 16 + hi * 8) * 2;
;     bf16x8 b0 = *reinterpret_cast<const bf16x8*>(Ks + KSWZ(r32, cb));
;     bf16x8 b1 = *reinterpret_cast<const bf16x8*>(Ks + KSWZ(32 + r32, cb));
;     p0 = __builtin_amdgcn_mfma_f32_32x32x16_bf16(b0, qr[d0], p0, 0, 0, 0);
;     p1 = __builtin_amdgcn_mfma_f32_32x32x16_bf16(b1, qr[d0], p1, 0, 0, 0); }
.LBB0_263:
	v_cndmask_b32_e64 v213, v160, v164, s[38:39]
	v_mul_f32_e32 v214, 0xbe0293ee, v213
	v_fmamk_f32 v80, v80, 0x3e0293ee, v214
	v_fmamk_f32 v81, v81, 0x3e0293ee, v214
	v_fmamk_f32 v82, v82, 0x3e0293ee, v214
	v_fmamk_f32 v83, v83, 0x3e0293ee, v214
	v_fmamk_f32 v84, v84, 0x3e0293ee, v214
	v_fmamk_f32 v85, v85, 0x3e0293ee, v214
	v_fmamk_f32 v86, v86, 0x3e0293ee, v214
	v_fmamk_f32 v87, v87, 0x3e0293ee, v214
	v_fmamk_f32 v88, v88, 0x3e0293ee, v214
	v_fmamk_f32 v89, v89, 0x3e0293ee, v214
	v_fmamk_f32 v90, v90, 0x3e0293ee, v214
	v_fmamk_f32 v91, v91, 0x3e0293ee, v214
	v_fmamk_f32 v92, v92, 0x3e0293ee, v214
	v_fmamk_f32 v93, v93, 0x3e0293ee, v214
	v_fmamk_f32 v94, v94, 0x3e0293ee, v214
	v_fmamk_f32 v95, v95, 0x3e0293ee, v214
	v_exp_f32_e32 v160, v80
	v_exp_f32_e32 v175, v81
	v_exp_f32_e32 v161, v82
	v_exp_f32_e32 v174, v83
	v_exp_f32_e32 v162, v84
	v_exp_f32_e32 v173, v85
	v_exp_f32_e32 v163, v86
	v_exp_f32_e32 v172, v87
	v_exp_f32_e32 v164, v88
	v_exp_f32_e32 v171, v89
	v_exp_f32_e32 v165, v90
	v_exp_f32_e32 v170, v91
	v_exp_f32_e32 v166, v92
	v_exp_f32_e32 v169, v93
	v_exp_f32_e32 v167, v94
	v_exp_f32_e32 v168, v95
	v_fmamk_f32 v223, v64, 0x3e0293ee, v214
	v_fmamk_f32 v224, v65, 0x3e0293ee, v214
	v_fmamk_f32 v225, v66, 0x3e0293ee, v214
	v_fmamk_f32 v226, v67, 0x3e0293ee, v214
	v_fmamk_f32 v227, v68, 0x3e0293ee, v214
	v_fmamk_f32 v216, v69, 0x3e0293ee, v214
	v_fmamk_f32 v217, v70, 0x3e0293ee, v214
	v_fmamk_f32 v218, v71, 0x3e0293ee, v214
	v_fmamk_f32 v219, v72, 0x3e0293ee, v214
	v_fmamk_f32 v220, v73, 0x3e0293ee, v214
	v_fmamk_f32 v221, v74, 0x3e0293ee, v214
	v_fmamk_f32 v222, v75, 0x3e0293ee, v214
	v_fmamk_f32 v215, v76, 0x3e0293ee, v214
	v_fmamk_f32 v228, v77, 0x3e0293ee, v214
	v_fmamk_f32 v229, v78, 0x3e0293ee, v214
	v_fmac_f32_e32 v214, 0x3e0293ee, v79
	s_add_i32 s19, s19, 2
	s_waitcnt lgkmcnt(0)
	ds_read_b128 v[64:67], v201 offset:32768
	ds_read_b128 v[68:71], v201 offset:40960
	ds_read_b128 v[230:233], v204 offset:32768
	ds_read_b128 v[234:237], v204 offset:40960
	ds_read_b128 v[240:243], v205 offset:32768
	ds_read_b128 v[246:249], v205 offset:40960
	v_exp_f32_e32 v194, v223
	v_exp_f32_e32 v223, v227
	s_waitcnt lgkmcnt(5)
	v_mfma_f32_32x32x16_bf16 v[80:95], v[64:67], v[100:103], 0
	v_exp_f32_e32 v227, v214
	v_add_f32_e32 v214, v175, v160
	v_add_f32_e32 v214, v161, v214
	v_add_f32_e32 v214, v174, v214
	v_add_f32_e32 v214, v162, v214
	v_add_f32_e32 v214, v173, v214
	s_waitcnt lgkmcnt(4)
	v_mfma_f32_32x32x16_bf16 v[64:79], v[68:71], v[100:103], 0
	v_add_f32_e32 v214, v163, v214
	v_add_f32_e32 v214, v172, v214
	v_add_f32_e32 v214, v164, v214
	v_add_f32_e32 v214, v171, v214
	v_add_f32_e32 v214, v165, v214
	v_add_f32_e32 v214, v170, v214
	v_add_f32_e32 v214, v166, v214
	s_waitcnt lgkmcnt(3)
	v_mfma_f32_32x32x16_bf16 v[80:95], v[230:233], v[108:111], v[80:95]
	v_exp_f32_e32 v195, v224
	v_add_f32_e32 v214, v169, v214
	v_exp_f32_e32 v196, v225
	v_add_f32_e32 v214, v167, v214
	v_exp_f32_e32 v197, v226
	v_add_f32_e32 v214, v168, v214
	v_add_f32_e32 v214, v194, v214
	s_waitcnt lgkmcnt(2)
	v_mfma_f32_32x32x16_bf16 v[64:79], v[234:237], v[108:111], v[64:79]
	ds_read_b128 v[230:233], v202 offset:32768
	ds_read_b128 v[234:237], v202 offset:40960
	v_exp_f32_e32 v216, v216
	v_add_f32_e32 v214, v195, v214
	v_exp_f32_e32 v217, v217
	v_add_f32_e32 v214, v196, v214
	v_exp_f32_e32 v218, v218
	v_add_f32_e32 v214, v197, v214
	s_waitcnt lgkmcnt(3)
	v_mfma_f32_32x32x16_bf16 v[80:95], v[240:243], v[96:99], v[80:95]
	v_exp_f32_e32 v219, v219
	v_add_f32_e32 v214, v223, v214
	v_exp_f32_e32 v220, v220
	v_add_f32_e32 v214, v216, v214
	v_exp_f32_e32 v221, v221
	v_add_f32_e32 v214, v217, v214
	v_exp_f32_e32 v222, v222
	s_waitcnt lgkmcnt(2)
	v_mfma_f32_32x32x16_bf16 v[64:79], v[246:249], v[96:99], v[64:79]
	ds_read_b128 v[240:243], v203 offset:32768
	ds_read_b128 v[246:249], v203 offset:40960
	v_add_f32_e32 v214, v218, v214
	v_exp_f32_e32 v224, v215
	v_add_f32_e32 v214, v219, v214
	v_exp_f32_e32 v225, v228
	v_add_f32_e32 v214, v220, v214
	v_exp_f32_e32 v226, v229
	s_waitcnt lgkmcnt(3)
	v_mfma_f32_32x32x16_bf16 v[80:95], v[230:233], v[104:107], v[80:95]
	v_add_f32_e32 v214, v221, v214
	v_add_f32_e32 v214, v222, v214
	v_add_f32_e32 v214, v224, v214
	v_add_f32_e32 v214, v225, v214
	v_add_f32_e32 v214, v226, v214
	v_add_f32_e32 v214, v227, v214
	v_mov_b32_e32 v215, v214
	s_waitcnt lgkmcnt(2)
	v_mfma_f32_32x32x16_bf16 v[64:79], v[234:237], v[104:107], v[64:79]
	ds_read_b128 v[230:233], v206 offset:32768
	ds_read_b128 v[234:237], v206 offset:40960
	v_permlane32_swap_b32_e32 v214, v215
	s_waitcnt lgkmcnt(3)
	v_mfma_f32_32x32x16_bf16 v[80:95], v[240:243], v[116:119], v[80:95]
	s_waitcnt lgkmcnt(2)
	v_mfma_f32_32x32x16_bf16 v[64:79], v[246:249], v[116:119], v[64:79]
	ds_read_b128 v[240:243], v207 offset:32768
	ds_read_b128 v[246:249], v207 offset:40960
	s_waitcnt lgkmcnt(3)
	v_mfma_f32_32x32x16_bf16 v[80:95], v[230:233], v[124:127], v[80:95]
	s_waitcnt lgkmcnt(2)
	v_mfma_f32_32x32x16_bf16 v[64:79], v[234:237], v[124:127], v[64:79]
	ds_read_b128 v[230:233], v208 offset:32768
	ds_read_b128 v[234:237], v208 offset:40960
	s_waitcnt lgkmcnt(3)
	v_mfma_f32_32x32x16_bf16 v[80:95], v[240:243], v[112:115], v[80:95]
	s_waitcnt lgkmcnt(2)
	v_mfma_f32_32x32x16_bf16 v[64:79], v[246:249], v[112:115], v[64:79]
	v_cvt_pk_bf16_f32 v160, v160, v175
	v_cvt_pk_bf16_f32 v161, v161, v174
	v_cvt_pk_bf16_f32 v162, v162, v173
	v_cvt_pk_bf16_f32 v163, v163, v172
	v_cvt_pk_bf16_f32 v164, v164, v171
	v_cvt_pk_bf16_f32 v165, v165, v170
	s_waitcnt lgkmcnt(1)
	v_mfma_f32_32x32x16_bf16 v[80:95], v[230:233], v[120:123], v[80:95]
	v_cvt_pk_bf16_f32 v166, v166, v169
	v_cvt_pk_bf16_f32 v167, v167, v168
	v_cvt_pk_bf16_f32 v168, v194, v195
	v_cvt_pk_bf16_f32 v169, v196, v197
	v_cvt_pk_bf16_f32 v170, v223, v216
	v_cvt_pk_bf16_f32 v171, v217, v218
	v_cvt_pk_bf16_f32 v172, v219, v220
	s_waitcnt lgkmcnt(0)
	v_mfma_f32_32x32x16_bf16 v[64:79], v[234:237], v[120:123], v[64:79]
	v_cvt_pk_bf16_f32 v173, v221, v222
	v_cvt_pk_bf16_f32 v174, v224, v225
	v_cvt_pk_bf16_f32 v175, v226, v227
	v_permlane32_swap_b32_e32 v160, v162
	v_permlane32_swap_b32_e32 v161, v163
	v_permlane32_swap_b32_e32 v164, v166
	v_permlane32_swap_b32_e32 v165, v167
	v_permlane32_swap_b32_e32 v168, v170
	v_permlane32_swap_b32_e32 v169, v171
	v_permlane32_swap_b32_e32 v172, v174
	v_permlane32_swap_b32_e32 v173, v175
	s_cmp_gt_u32 s19, 60
	s_cselect_b64 s[42:43], -1, 0
	s_and_b64 vcc, exec, s[42:43]
	s_cbranch_vccnz .LBB0_265
	s_mov_b32 s20, 0xfffb0000
	s_mov_b32 s21, -1
	v_lshl_add_u64 v[132:133], v[182:183], 0, s[20:21]
	s_mov_b32 s20, 0x50000
	s_mov_b32 s21, 0
	v_lshl_add_u64 v[250:251], v[182:183], 0, s[20:21]
	global_load_dwordx4 v[128:131], v[132:133], off
	global_load_dwordx4 v[136:139], v[250:251], off offset:-1024
	global_load_dwordx4 v[132:135], v[182:183], off
	s_mov_b32 s20, 0xa0000
	v_lshl_add_u64 v[250:251], v[182:183], 0, s[20:21]
	global_load_dwordx4 v[140:143], v[250:251], off offset:-1024
; #define SBAR() __builtin_amdgcn_sched_barrier(0)
; __device__ __forceinline__ void partialSM(f32x16& p0, f32x16& p1, float& m_reg, float& mn, float& alpha) {
;   constexpr float C = SCALE * 1.4426950408889634f;
;   float pmax = p0[0]; for (int r = 1; r < 16; ++r) pmax = fmaxf(pmax, p0[r]); for (int r = 0; r < 16; ++r) pmax = fmaxf(pmax, p1[r]);
;   { auto rr = __builtin_amdgcn_permlane32_swap(__float_as_uint(pmax), __float_as_uint(pmax), false, false);
;     pmax = fmaxf(__uint_as_float(rr[0]), __uint_as_float(rr[1])); }
;   if (__builtin_expect(__all(pmax - m_reg <= THR / SCALE), 1)) { mn = m_reg; alpha = 1.f; }
;   else { mn = fmaxf(m_reg, pmax); alpha = __builtin_amdgcn_exp2f((m_reg - mn) * C); m_reg = mn; }
; template <int D0> __device__ __forceinline__ void pv_one(f32x16& od, int vb, bf16x8 pa0, bf16x8 pa1, bf16x8 pa2, bf16x8 pa3) {
;   const s16x4 l0 = tr_read<v_rd_off(D0, 0, 0)>(vb), h0 = tr_read<v_rd_off(D0, 0, 1)>(vb), l1 = tr_read<v_rd_off(D0, 1, 0)>(vb), h1 = tr_read<v_rd_off(D0, 1, 1)>(vb);
;   const s16x4 l2 = tr_read<v_rd_off(D0, 2, 0)>(vb), h2 = tr_read<v_rd_off(D0, 2, 1)>(vb), l3 = tr_read<v_rd_off(D0, 3, 0)>(vb), h3 = tr_read<v_rd_off(D0, 3, 1)>(vb);
;   asm volatile("s_waitcnt lgkmcnt(0)" ::: "memory"); SBAR();
;     ...
;   od = __builtin_amdgcn_mfma_f32_32x32x16_bf16(pa0, PK(l0, h0), od, 0, 0, 0);
;   od = __builtin_amdgcn_mfma_f32_32x32x16_bf16(pa1, PK(l1, h1), od, 0, 0, 0);
;   od = __builtin_amdgcn_mfma_f32_32x32x16_bf16(pa2, PK(l2, h2), od, 0, 0, 0);
;   od = __builtin_amdgcn_mfma_f32_32x32x16_bf16(pa3, PK(l3, h3), od, 0, 0, 0);
;     ...
; }
; __device__ __forceinline__ void pv_d0(f32x16* o, int vb, bf16x8 pa0, bf16x8 pa1, bf16x8 pa2, bf16x8 pa3) {
;   pv_one<0>(o[0], vb, pa0, pa1, pa2, pa3); pv_one<1>(o[1], vb, pa0, pa1, pa2, pa3); pv_one<2>(o[2], vb, pa0, pa1, pa2, pa3); pv_one<3>(o[3], vb, pa0, pa1, pa2, pa3);
.LBB0_265:
	ds_read_b64_tr_b16 v[216:217], v190 offset:0
	ds_read_b64_tr_b16 v[218:219], v190 offset:0x800
	ds_read_b64_tr_b16 v[220:221], v190 offset:0x1000
	ds_read_b64_tr_b16 v[222:223], v190 offset:0x1800
	ds_read_b64_tr_b16 v[224:225], v190 offset:0x2000
	ds_read_b64_tr_b16 v[226:227], v190 offset:0x2800
	ds_read_b64_tr_b16 v[228:229], v190 offset:0x3000
	ds_read_b64_tr_b16 v[230:231], v190 offset:0x3800
	s_waitcnt lgkmcnt(0)
	s_nop 0
	v_mfma_f32_32x32x16_bf16 v[0:15], v[160:163], v[216:219], v[0:15]
	ds_read_b64_tr_b16 v[216:217], v190 offset:0x200
	ds_read_b64_tr_b16 v[218:219], v190 offset:0xa00
	v_mfma_f32_32x32x16_bf16 v[0:15], v[164:167], v[220:223], v[0:15]
	ds_read_b64_tr_b16 v[220:221], v190 offset:0x1200
	ds_read_b64_tr_b16 v[222:223], v190 offset:0x1a00
	v_mfma_f32_32x32x16_bf16 v[0:15], v[168:171], v[224:227], v[0:15]
	ds_read_b64_tr_b16 v[224:225], v190 offset:0x2200
	ds_read_b64_tr_b16 v[226:227], v190 offset:0x2a00
	v_mfma_f32_32x32x16_bf16 v[0:15], v[172:175], v[228:231], v[0:15]
	ds_read_b64_tr_b16 v[228:229], v190 offset:0x3200
	ds_read_b64_tr_b16 v[230:231], v190 offset:0x3a00
	s_waitcnt lgkmcnt(0)
	v_mfma_f32_32x32x16_bf16 v[48:63], v[160:163], v[216:219], v[48:63]
	ds_read_b64_tr_b16 v[216:217], v190 offset:0x400
	ds_read_b64_tr_b16 v[218:219], v190 offset:0xc00
	v_mfma_f32_32x32x16_bf16 v[48:63], v[164:167], v[220:223], v[48:63]
	ds_read_b64_tr_b16 v[220:221], v190 offset:0x1400
	ds_read_b64_tr_b16 v[222:223], v190 offset:0x1c00
	v_mfma_f32_32x32x16_bf16 v[48:63], v[168:171], v[224:227], v[48:63]
	ds_read_b64_tr_b16 v[224:225], v190 offset:0x2400
	ds_read_b64_tr_b16 v[226:227], v190 offset:0x2c00
	v_mfma_f32_32x32x16_bf16 v[48:63], v[172:175], v[228:231], v[48:63]
	ds_read_b64_tr_b16 v[228:229], v190 offset:0x3400
	ds_read_b64_tr_b16 v[230:231], v190 offset:0x3c00
	s_waitcnt lgkmcnt(0)
	v_mfma_f32_32x32x16_bf16 v[32:47], v[160:163], v[216:219], v[32:47]
	ds_read_b64_tr_b16 v[216:217], v190 offset:0x600
	ds_read_b64_tr_b16 v[218:219], v190 offset:0xe00
	v_mfma_f32_32x32x16_bf16 v[32:47], v[164:167], v[220:223], v[32:47]
	ds_read_b64_tr_b16 v[220:221], v190 offset:0x1600
	ds_read_b64_tr_b16 v[222:223], v190 offset:0x1e00
	v_mfma_f32_32x32x16_bf16 v[32:47], v[168:171], v[224:227], v[32:47]
	ds_read_b64_tr_b16 v[224:225], v190 offset:0x2600
	ds_read_b64_tr_b16 v[226:227], v190 offset:0x2e00
	v_mfma_f32_32x32x16_bf16 v[32:47], v[172:175], v[228:231], v[32:47]
	ds_read_b64_tr_b16 v[228:229], v190 offset:0x3600
	ds_read_b64_tr_b16 v[230:231], v190 offset:0x3e00
	s_waitcnt lgkmcnt(0)
	v_mfma_f32_32x32x16_bf16 v[16:31], v[160:163], v[216:219], v[16:31]
	v_max_f32_e32 v160, v80, v81
	v_max3_f32 v160, v160, v82, v83
	v_max3_f32 v160, v160, v84, v85
	v_max3_f32 v160, v160, v86, v87
	v_max3_f32 v160, v160, v88, v89
	v_max3_f32 v160, v160, v90, v91
	v_max3_f32 v160, v160, v92, v93
	v_mfma_f32_32x32x16_bf16 v[16:31], v[164:167], v[220:223], v[16:31]
	v_max3_f32 v160, v160, v94, v95
	v_max3_f32 v160, v160, v64, v65
	v_max3_f32 v160, v160, v66, v67
	v_max3_f32 v160, v160, v68, v69
	v_max3_f32 v160, v160, v70, v71
	v_max3_f32 v160, v160, v72, v73
	v_max3_f32 v160, v160, v74, v75
	v_max3_f32 v160, v160, v76, v77
	v_mfma_f32_32x32x16_bf16 v[16:31], v[168:171], v[224:227], v[16:31]
	v_max3_f32 v160, v160, v78, v79
	v_mov_b32_e32 v161, v160
	s_nop 1
	v_permlane32_swap_b32_e32 v160, v161
	v_max_f32_e32 v160, v160, v161
	v_sub_f32_e32 v161, v160, v213
	v_cmp_ge_f32_e32 vcc, s71, v161
	v_max_f32_e32 v161, v213, v160
	v_mfma_f32_32x32x16_bf16 v[16:31], v[172:175], v[228:231], v[16:31]
	v_sub_f32_e32 v160, v213, v161
	v_mul_f32_e32 v160, 0x3e0293ee, v160
	v_exp_f32_e32 v160, v160
	s_cmp_eq_u64 vcc, exec
	s_cselect_b64 s[38:39], -1, 0
	s_barrier
	s_waitcnt vmcnt(4)
	v_cndmask_b32_e64 v160, v160, 1.0, s[38:39]
	v_cmp_gt_f32_e32 vcc, 1.0, v160
	s_waitcnt vmcnt(3)
	ds_write_b128 v192, v[144:147] offset:16384
	s_waitcnt vmcnt(1)
	ds_write_b128 v193, v[156:159] offset:16384
	ds_write_b128 v199, v[148:151] offset:32768
	s_waitcnt vmcnt(0)
	ds_write_b128 v200, v[152:155] offset:32768
	s_cbranch_vccz .LBB0_269
	s_and_saveexec_b64 s[44:45], s[36:37]
	ds_write_b32 v188, v160 offset:128
	s_or_b64 exec, exec, s[44:45]
	s_waitcnt lgkmcnt(0)
	v_add_u32_e32 v156, v187, v176
	ds_read_b128 v[144:147], v156 offset:224
	ds_read_b128 v[148:151], v156 offset:192
	ds_read_b128 v[152:155], v156 offset:160
	ds_read_b128 v[156:159], v156 offset:128
	s_waitcnt lgkmcnt(3)
	v_pk_mul_f32 v[12:13], v[12:13], v[144:145]
	s_waitcnt lgkmcnt(2)
	v_pk_mul_f32 v[8:9], v[8:9], v[148:149]
	s_waitcnt lgkmcnt(1)
	v_pk_mul_f32 v[4:5], v[4:5], v[152:153]
	v_pk_mul_f32 v[14:15], v[14:15], v[146:147]
	v_pk_mul_f32 v[10:11], v[10:11], v[150:151]
	v_pk_mul_f32 v[6:7], v[6:7], v[154:155]
	s_waitcnt lgkmcnt(0)
	v_pk_mul_f32 v[2:3], v[2:3], v[158:159]
	v_pk_mul_f32 v[0:1], v[0:1], v[156:157]
	v_pk_mul_f32 v[60:61], v[60:61], v[144:145]
	v_pk_mul_f32 v[56:57], v[56:57], v[148:149]
	v_pk_mul_f32 v[52:53], v[52:53], v[152:153]
	v_pk_mul_f32 v[62:63], v[62:63], v[146:147]
	v_pk_mul_f32 v[58:59], v[58:59], v[150:151]
	v_pk_mul_f32 v[54:55], v[54:55], v[154:155]
	v_pk_mul_f32 v[50:51], v[50:51], v[158:159]
	v_pk_mul_f32 v[48:49], v[48:49], v[156:157]
	v_pk_mul_f32 v[44:45], v[44:45], v[144:145]
	v_pk_mul_f32 v[40:41], v[40:41], v[148:149]
	v_pk_mul_f32 v[36:37], v[36:37], v[152:153]
	v_pk_mul_f32 v[46:47], v[46:47], v[146:147]
	v_pk_mul_f32 v[42:43], v[42:43], v[150:151]
	v_pk_mul_f32 v[38:39], v[38:39], v[154:155]
	v_pk_mul_f32 v[34:35], v[34:35], v[158:159]
	v_pk_mul_f32 v[32:33], v[32:33], v[156:157]
	v_pk_mul_f32 v[28:29], v[28:29], v[144:145]
	v_pk_mul_f32 v[24:25], v[24:25], v[148:149]
	v_pk_mul_f32 v[20:21], v[20:21], v[152:153]
	v_pk_mul_f32 v[30:31], v[30:31], v[146:147]
	v_pk_mul_f32 v[26:27], v[26:27], v[150:151]
	v_pk_mul_f32 v[22:23], v[22:23], v[154:155]
	v_pk_mul_f32 v[18:19], v[18:19], v[158:159]
	v_pk_mul_f32 v[16:17], v[16:17], v[156:157]

;     __device__ __forceinline__ void operator()(f32x4 (&acc)[2][2][4][2], const Unit& u, int wr, int wc, int fr, int fq, LAS unsigned char* lds) const {
;     ...
;             for (int m = 0; m < 4; ++m) { float sv = 0.f, qv = 0.f;
; #pragma unroll
;                 for (int bj = 0; bj < 2; ++bj)
; #pragma unroll
;                     for (int n = 0; n < 2; ++n) { const f32x4 x = acc[ai][bj][m][n]; sv += (x[0] + x[1]) + (x[2] + x[3]); qv += (x[0] * x[0] + x[1] * x[1]) + (x[2] * x[2] + x[3] * x[3]); }
;                 sv += __shfl_xor(sv, 16); sv += __shfl_xor(sv, 32); qv += __shfl_xor(qv, 16); qv += __shfl_xor(qv, 32);
;                 if (fq == 0) P[(ai * HALF + wr * 64 + m * 16 + fr) * 4 + wc] = (f32x2){sv, qv};
;                 __builtin_amdgcn_sched_barrier(0); }
;     ...
;                     for (int n = 0; n < 2; ++n) { const f32x4 gn = *(const f32x4*)(gain + col0 + bj * HALF + n * 16), bs = *(const f32x4*)(bias + col0 + bj * HALF + n * 16);
.LBB0_369:
	global_load_dwordx4 v[204:207], v[138:139], off
	global_load_dwordx4 v[208:211], v[138:139], off offset:64
	global_load_dwordx4 v[212:215], v[138:139], off offset:512
	global_load_dwordx4 v[216:219], v[138:139], off offset:576
	global_load_dwordx4 v[220:223], v[140:141], off
	global_load_dwordx4 v[224:227], v[140:141], off offset:64
	global_load_dwordx4 v[228:231], v[140:141], off offset:512
	global_load_dwordx4 v[232:235], v[140:141], off offset:576
	v_and_b32_e32 v147, 64, v198
	v_xor_b32_e32 v146, 16, v198
	v_add_u32_e32 v176, 64, v147
	v_cmp_lt_i32_e32 vcc, v146, v176
	v_mul_f32_e32 v150, v122, v122
	v_add_f32_e32 v148, v126, v127
	v_cndmask_b32_e32 v146, v198, v146, vcc
	v_lshlrev_b32_e32 v151, 2, v146
	v_add_f32_e32 v146, v124, v125
	v_mul_f32_e32 v173, v124, v124
	v_mul_f32_e32 v175, v125, v125
	v_mul_f32_e32 v179, v126, v126
	v_mul_f32_e32 v181, v127, v127
	v_mul_f32_e32 v147, v120, v120
	v_mul_f32_e32 v149, v121, v121
	v_pk_fma_f32 v[182:183], v[122:123], v[122:123], v[150:151] op_sel_hi:[1,1,0]
	v_mov_b32_e32 v172, v120
	v_mov_b32_e32 v174, v121
	v_mov_b32_e32 v178, v122
	v_mov_b32_e32 v180, v123
	v_pk_add_f32 v[172:173], v[172:173], v[174:175]
	v_pk_add_f32 v[174:175], v[178:179], v[180:181]
	v_pk_add_f32 v[146:147], v[146:147], v[148:149]
	v_mov_b32_e32 v182, v177
	v_mul_f32_e32 v185, v116, v116
	v_mul_f32_e32 v187, v117, v117
	v_mul_f32_e32 v189, v118, v118
	v_mul_f32_e32 v191, v119, v119
	v_pk_add_f32 v[172:173], v[172:173], v[174:175]
	v_pk_add_f32 v[146:147], v[146:147], v[182:183]
	v_mov_b32_e32 v184, v116
	v_mov_b32_e32 v186, v117
	v_mov_b32_e32 v188, v118
	v_mov_b32_e32 v190, v119
	v_pk_add_f32 v[146:147], v[172:173], v[146:147]
	v_pk_add_f32 v[148:149], v[184:185], v[186:187]
	v_pk_add_f32 v[172:173], v[188:189], v[190:191]
	v_mul_f32_e32 v193, v112, v112
	v_mul_f32_e32 v195, v113, v113
	v_mul_f32_e32 v197, v114, v114
	v_mul_f32_e32 v201, v115, v115
	v_pk_add_f32 v[148:149], v[148:149], v[172:173]
	v_mov_b32_e32 v192, v112
	v_mov_b32_e32 v194, v113
	v_mov_b32_e32 v196, v114
	v_mov_b32_e32 v200, v115
	v_pk_add_f32 v[146:147], v[146:147], v[148:149]
	v_pk_add_f32 v[148:149], v[192:193], v[194:195]
	v_pk_add_f32 v[172:173], v[196:197], v[200:201]
	v_xor_b32_e32 v150, 32, v198
	v_pk_add_f32 v[148:149], v[148:149], v[172:173]
	v_cmp_lt_i32_e32 vcc, v150, v176
	v_pk_add_f32 v[146:147], v[146:147], v[148:149]
	v_mov_b32_e32 v148, v146
	v_mov_b32_e32 v149, v147
	s_nop 1
	v_permlane16_swap_b32_e32 v146, v148
	v_permlane16_swap_b32_e32 v147, v149
	v_cndmask_b32_e32 v150, v198, v150, vcc
	v_lshlrev_b32_e32 v172, 2, v150
	v_mov_b32_e32 v150, v252
	v_pk_add_f32 v[146:147], v[146:147], v[148:149]
	v_mov_b32_e32 v148, v146
	v_mov_b32_e32 v149, v147
	s_nop 1
	v_permlane32_swap_b32_e32 v146, v148
	v_permlane32_swap_b32_e32 v147, v149
	v_readfirstlane_b32 s22, v150
	s_and_saveexec_b64 s[40:41], s[36:37]
	s_cbranch_execz .LBB0_371
	v_pk_add_f32 v[146:147], v[146:147], v[148:149]
	ds_write_b64 v171, v[146:147]
.LBB0_371:
	s_or_b64 exec, exec, s[40:41]
	v_mul_f32_e32 v175, v108, v108
	v_mul_f32_e32 v174, v106, v106
	v_add_f32_e32 v146, v108, v109
	s_waitcnt lgkmcnt(0)
	v_add_f32_e32 v148, v110, v111
	v_mul_f32_e32 v179, v109, v109
	v_mul_f32_e32 v181, v110, v110
	v_mul_f32_e32 v183, v111, v111
	v_mul_f32_e32 v147, v104, v104
	v_mul_f32_e32 v149, v105, v105
	v_pk_fma_f32 v[184:185], v[106:107], v[106:107], v[174:175] op_sel_hi:[1,1,0]
	v_mov_b32_e32 v174, v104
	v_mov_b32_e32 v178, v105
	v_mov_b32_e32 v180, v106
	v_mov_b32_e32 v182, v107
	v_pk_add_f32 v[174:175], v[174:175], v[178:179]
	v_pk_add_f32 v[178:179], v[180:181], v[182:183]
	v_pk_add_f32 v[146:147], v[146:147], v[148:149]
	v_mov_b32_e32 v184, v177
	v_mul_f32_e32 v187, v100, v100
	v_mul_f32_e32 v189, v101, v101
	v_mul_f32_e32 v191, v102, v102
	v_mul_f32_e32 v193, v103, v103
	v_pk_add_f32 v[174:175], v[174:175], v[178:179]
	v_pk_add_f32 v[146:147], v[146:147], v[184:185]
	v_mov_b32_e32 v186, v100
	v_mov_b32_e32 v188, v101
	v_mov_b32_e32 v190, v102
	v_mov_b32_e32 v192, v103
	v_pk_add_f32 v[146:147], v[174:175], v[146:147]
	v_pk_add_f32 v[148:149], v[186:187], v[188:189]
	v_pk_add_f32 v[174:175], v[190:191], v[192:193]
	v_mul_f32_e32 v195, v96, v96
	v_mul_f32_e32 v197, v97, v97
	v_mul_f32_e32 v201, v98, v98
	v_mul_f32_e32 v203, v99, v99
	v_pk_add_f32 v[148:149], v[148:149], v[174:175]
	v_mov_b32_e32 v194, v96
	v_mov_b32_e32 v196, v97
	v_mov_b32_e32 v200, v98
	v_mov_b32_e32 v202, v99
	v_pk_add_f32 v[146:147], v[146:147], v[148:149]
	v_pk_add_f32 v[148:149], v[194:195], v[196:197]
	v_pk_add_f32 v[174:175], v[200:201], v[202:203]
	s_nop 0
	v_pk_add_f32 v[148:149], v[148:149], v[174:175]
	s_nop 0
	v_pk_add_f32 v[146:147], v[146:147], v[148:149]
	v_mov_b32_e32 v148, v146
	v_mov_b32_e32 v149, v147
	s_nop 1
	v_permlane16_swap_b32_e32 v146, v148
	v_permlane16_swap_b32_e32 v147, v149
	v_pk_add_f32 v[146:147], v[146:147], v[148:149]
	v_mov_b32_e32 v148, v146
	v_mov_b32_e32 v149, v147
	s_nop 1
	v_permlane32_swap_b32_e32 v146, v148
	v_permlane32_swap_b32_e32 v147, v149
	s_and_saveexec_b64 s[40:41], s[36:37]
	s_cbranch_execz .LBB0_373
	v_pk_add_f32 v[146:147], v[146:147], v[148:149]
	ds_write_b64 v171, v[146:147] offset:512
;     __device__ __forceinline__ void operator()(f32x4 (&acc)[2][2][4][2], const Unit& u, int wr, int wc, int fr, int fq, LAS unsigned char* lds) const {
;     ...
;             for (int m = 0; m < 4; ++m) { float sv = 0.f, qv = 0.f;
; #pragma unroll
;                 for (int bj = 0; bj < 2; ++bj)
; #pragma unroll
;                     for (int n = 0; n < 2; ++n) { const f32x4 x = acc[ai][bj][m][n]; sv += (x[0] + x[1]) + (x[2] + x[3]); qv += (x[0] * x[0] + x[1] * x[1]) + (x[2] * x[2] + x[3] * x[3]); }
;                 sv += __shfl_xor(sv, 16); sv += __shfl_xor(sv, 32); qv += __shfl_xor(qv, 16); qv += __shfl_xor(qv, 32);
;                 if (fq == 0) P[(ai * HALF + wr * 64 + m * 16 + fr) * 4 + wc] = (f32x2){sv, qv};
;                 __builtin_amdgcn_sched_barrier(0); }
.LBB0_373:
	s_or_b64 exec, exec, s[40:41]
	v_mul_f32_e32 v175, v92, v92
	v_mul_f32_e32 v174, v90, v90
	v_add_f32_e32 v146, v92, v93
	s_waitcnt lgkmcnt(0)
	v_add_f32_e32 v148, v94, v95
	v_mul_f32_e32 v179, v93, v93
	v_mul_f32_e32 v181, v94, v94
	v_mul_f32_e32 v183, v95, v95
	v_mul_f32_e32 v147, v88, v88
	v_mul_f32_e32 v149, v89, v89
	v_pk_fma_f32 v[184:185], v[90:91], v[90:91], v[174:175] op_sel_hi:[1,1,0]
	v_mov_b32_e32 v174, v88
	v_mov_b32_e32 v178, v89
	v_mov_b32_e32 v180, v90
	v_mov_b32_e32 v182, v91
	v_pk_add_f32 v[174:175], v[174:175], v[178:179]
	v_pk_add_f32 v[178:179], v[180:181], v[182:183]
	v_pk_add_f32 v[146:147], v[146:147], v[148:149]
	v_mov_b32_e32 v184, v177
	v_mul_f32_e32 v187, v84, v84
	v_mul_f32_e32 v189, v85, v85
	v_mul_f32_e32 v191, v86, v86
	v_mul_f32_e32 v193, v87, v87
	v_pk_add_f32 v[174:175], v[174:175], v[178:179]
	v_pk_add_f32 v[146:147], v[146:147], v[184:185]
	v_mov_b32_e32 v186, v84
	v_mov_b32_e32 v188, v85
	v_mov_b32_e32 v190, v86
	v_mov_b32_e32 v192, v87
	v_pk_add_f32 v[146:147], v[174:175], v[146:147]
	v_pk_add_f32 v[148:149], v[186:187], v[188:189]
	v_pk_add_f32 v[174:175], v[190:191], v[192:193]
	v_mul_f32_e32 v195, v80, v80
	v_mul_f32_e32 v197, v81, v81
	v_mul_f32_e32 v201, v82, v82
	v_mul_f32_e32 v203, v83, v83
	v_pk_add_f32 v[148:149], v[148:149], v[174:175]
	v_mov_b32_e32 v194, v80
	v_mov_b32_e32 v196, v81
	v_mov_b32_e32 v200, v82
	v_mov_b32_e32 v202, v83
	v_pk_add_f32 v[146:147], v[146:147], v[148:149]
	v_pk_add_f32 v[148:149], v[194:195], v[196:197]
	v_pk_add_f32 v[174:175], v[200:201], v[202:203]
	s_nop 0
	v_pk_add_f32 v[148:149], v[148:149], v[174:175]
	s_nop 0
	v_pk_add_f32 v[146:147], v[146:147], v[148:149]
	v_mov_b32_e32 v148, v146
	v_mov_b32_e32 v149, v147
	s_nop 1
	v_permlane16_swap_b32_e32 v146, v148
	v_permlane16_swap_b32_e32 v147, v149
	v_pk_add_f32 v[146:147], v[146:147], v[148:149]
	v_mov_b32_e32 v148, v146
	v_mov_b32_e32 v149, v147
	s_nop 1
	v_permlane32_swap_b32_e32 v146, v148
	v_permlane32_swap_b32_e32 v147, v149
	s_and_saveexec_b64 s[40:41], s[36:37]
	s_cbranch_execz .LBB0_375
	v_pk_add_f32 v[146:147], v[146:147], v[148:149]
	ds_write_b64 v171, v[146:147] offset:1024
.LBB0_375:
	s_or_b64 exec, exec, s[40:41]
	v_mul_f32_e32 v175, v76, v76
	v_mul_f32_e32 v174, v74, v74
	v_add_f32_e32 v146, v76, v77
	s_waitcnt lgkmcnt(0)
	v_add_f32_e32 v148, v78, v79
	v_mul_f32_e32 v179, v77, v77
	v_mul_f32_e32 v181, v78, v78
	v_mul_f32_e32 v183, v79, v79
	v_mul_f32_e32 v147, v72, v72
	v_mul_f32_e32 v149, v73, v73
	v_pk_fma_f32 v[184:185], v[74:75], v[74:75], v[174:175] op_sel_hi:[1,1,0]
	v_mov_b32_e32 v174, v72
	v_mov_b32_e32 v178, v73
	v_mov_b32_e32 v180, v74
	v_mov_b32_e32 v182, v75
	v_pk_add_f32 v[174:175], v[174:175], v[178:179]
	v_pk_add_f32 v[178:179], v[180:181], v[182:183]
	v_pk_add_f32 v[146:147], v[146:147], v[148:149]
	v_mov_b32_e32 v184, v177
	v_mul_f32_e32 v187, v68, v68
	v_mul_f32_e32 v189, v69, v69
	v_mul_f32_e32 v191, v70, v70
	v_mul_f32_e32 v193, v71, v71
	v_pk_add_f32 v[174:175], v[174:175], v[178:179]
	v_pk_add_f32 v[146:147], v[146:147], v[184:185]
	v_mov_b32_e32 v186, v68
	v_mov_b32_e32 v188, v69
	v_mov_b32_e32 v190, v70
	v_mov_b32_e32 v192, v71
	v_pk_add_f32 v[146:147], v[174:175], v[146:147]
	v_pk_add_f32 v[148:149], v[186:187], v[188:189]
	v_pk_add_f32 v[174:175], v[190:191], v[192:193]
	v_mul_f32_e32 v195, v64, v64
	v_mul_f32_e32 v197, v65, v65
	v_mul_f32_e32 v201, v66, v66
	v_mul_f32_e32 v203, v67, v67
	v_pk_add_f32 v[148:149], v[148:149], v[174:175]
	v_mov_b32_e32 v194, v64
	v_mov_b32_e32 v196, v65
	v_mov_b32_e32 v200, v66
	v_mov_b32_e32 v202, v67
	v_pk_add_f32 v[146:147], v[146:147], v[148:149]
	v_pk_add_f32 v[148:149], v[194:195], v[196:197]
	v_pk_add_f32 v[174:175], v[200:201], v[202:203]
	s_nop 0
	v_pk_add_f32 v[148:149], v[148:149], v[174:175]
	s_nop 0
	v_pk_add_f32 v[146:147], v[146:147], v[148:149]
	v_mov_b32_e32 v148, v146
	v_mov_b32_e32 v149, v147
	s_nop 1
	v_permlane16_swap_b32_e32 v146, v148
	v_permlane16_swap_b32_e32 v147, v149
	v_pk_add_f32 v[146:147], v[146:147], v[148:149]
	v_mov_b32_e32 v148, v146
	v_mov_b32_e32 v149, v147
	s_nop 1
	v_permlane32_swap_b32_e32 v146, v148
	v_permlane32_swap_b32_e32 v147, v149
	s_and_saveexec_b64 s[40:41], s[36:37]
	s_cbranch_execz .LBB0_377
	v_pk_add_f32 v[146:147], v[146:147], v[148:149]
	ds_write_b64 v171, v[146:147] offset:1536
.LBB0_377:
	s_or_b64 exec, exec, s[40:41]
	v_mul_f32_e32 v175, v60, v60
	v_mul_f32_e32 v174, v58, v58
	v_add_f32_e32 v146, v60, v61
	s_waitcnt lgkmcnt(0)
	v_add_f32_e32 v148, v62, v63
	v_mul_f32_e32 v179, v61, v61
	v_mul_f32_e32 v181, v62, v62
	v_mul_f32_e32 v183, v63, v63
	v_mul_f32_e32 v147, v56, v56
	v_mul_f32_e32 v149, v57, v57
	v_pk_fma_f32 v[184:185], v[58:59], v[58:59], v[174:175] op_sel_hi:[1,1,0]
	v_mov_b32_e32 v174, v56
	v_mov_b32_e32 v178, v57
	v_mov_b32_e32 v180, v58
	v_mov_b32_e32 v182, v59
	v_pk_add_f32 v[174:175], v[174:175], v[178:179]
	v_pk_add_f32 v[178:179], v[180:181], v[182:183]
	v_pk_add_f32 v[146:147], v[146:147], v[148:149]
	v_mov_b32_e32 v184, v177
	v_mul_f32_e32 v187, v52, v52
	v_mul_f32_e32 v189, v53, v53
	v_mul_f32_e32 v191, v54, v54
	v_mul_f32_e32 v193, v55, v55
	v_pk_add_f32 v[174:175], v[174:175], v[178:179]
	v_pk_add_f32 v[146:147], v[146:147], v[184:185]
	v_mov_b32_e32 v186, v52
	v_mov_b32_e32 v188, v53
	v_mov_b32_e32 v190, v54
	v_mov_b32_e32 v192, v55
	v_pk_add_f32 v[146:147], v[174:175], v[146:147]
	v_pk_add_f32 v[148:149], v[186:187], v[188:189]
	v_pk_add_f32 v[174:175], v[190:191], v[192:193]
	v_mul_f32_e32 v195, v48, v48
	v_mul_f32_e32 v197, v49, v49
	v_mul_f32_e32 v201, v50, v50
	v_mul_f32_e32 v203, v51, v51
	v_pk_add_f32 v[148:149], v[148:149], v[174:175]
	v_mov_b32_e32 v194, v48
	v_mov_b32_e32 v196, v49
	v_mov_b32_e32 v200, v50
	v_mov_b32_e32 v202, v51
	v_pk_add_f32 v[146:147], v[146:147], v[148:149]
	v_pk_add_f32 v[148:149], v[194:195], v[196:197]
	v_pk_add_f32 v[174:175], v[200:201], v[202:203]
	s_nop 0
	v_pk_add_f32 v[148:149], v[148:149], v[174:175]
	s_nop 0
	v_pk_add_f32 v[146:147], v[146:147], v[148:149]
	v_mov_b32_e32 v148, v146
	v_mov_b32_e32 v149, v147
	s_nop 1
	v_permlane16_swap_b32_e32 v146, v148
	v_permlane16_swap_b32_e32 v147, v149
	v_pk_add_f32 v[146:147], v[146:147], v[148:149]
	v_mov_b32_e32 v148, v146
	v_mov_b32_e32 v149, v147
	s_nop 1
	v_permlane32_swap_b32_e32 v146, v148
	v_permlane32_swap_b32_e32 v147, v149
	s_and_saveexec_b64 s[40:41], s[36:37]
	s_cbranch_execz .LBB0_379
	v_pk_add_f32 v[146:147], v[146:147], v[148:149]
	ds_write_b64 v171, v[146:147] offset:4096
;     __device__ __forceinline__ void operator()(f32x4 (&acc)[2][2][4][2], const Unit& u, int wr, int wc, int fr, int fq, LAS unsigned char* lds) const {
;     ...
;             for (int m = 0; m < 4; ++m) { float sv = 0.f, qv = 0.f;
; #pragma unroll
;                 for (int bj = 0; bj < 2; ++bj)
; #pragma unroll
;                     for (int n = 0; n < 2; ++n) { const f32x4 x = acc[ai][bj][m][n]; sv += (x[0] + x[1]) + (x[2] + x[3]); qv += (x[0] * x[0] + x[1] * x[1]) + (x[2] * x[2] + x[3] * x[3]); }
;                 sv += __shfl_xor(sv, 16); sv += __shfl_xor(sv, 32); qv += __shfl_xor(qv, 16); qv += __shfl_xor(qv, 32);
;                 if (fq == 0) P[(ai * HALF + wr * 64 + m * 16 + fr) * 4 + wc] = (f32x2){sv, qv};
;                 __builtin_amdgcn_sched_barrier(0); }
.LBB0_379:
	s_or_b64 exec, exec, s[40:41]
	v_mul_f32_e32 v175, v44, v44
	v_mul_f32_e32 v174, v42, v42
	v_add_f32_e32 v146, v44, v45
	s_waitcnt lgkmcnt(0)
	v_add_f32_e32 v148, v46, v47
	v_mul_f32_e32 v179, v45, v45
	v_mul_f32_e32 v181, v46, v46
	v_mul_f32_e32 v183, v47, v47
	v_mul_f32_e32 v147, v40, v40
	v_mul_f32_e32 v149, v41, v41
	v_pk_fma_f32 v[184:185], v[42:43], v[42:43], v[174:175] op_sel_hi:[1,1,0]
	v_mov_b32_e32 v174, v40
	v_mov_b32_e32 v178, v41
	v_mov_b32_e32 v180, v42
	v_mov_b32_e32 v182, v43
	v_pk_add_f32 v[174:175], v[174:175], v[178:179]
	v_pk_add_f32 v[178:179], v[180:181], v[182:183]
	v_pk_add_f32 v[146:147], v[146:147], v[148:149]
	v_mov_b32_e32 v184, v177
	v_mul_f32_e32 v187, v36, v36
	v_mul_f32_e32 v189, v37, v37
	v_mul_f32_e32 v191, v38, v38
	v_mul_f32_e32 v193, v39, v39
	v_pk_add_f32 v[174:175], v[174:175], v[178:179]
	v_pk_add_f32 v[146:147], v[146:147], v[184:185]
	v_mov_b32_e32 v186, v36
	v_mov_b32_e32 v188, v37
	v_mov_b32_e32 v190, v38
	v_mov_b32_e32 v192, v39
	v_pk_add_f32 v[146:147], v[174:175], v[146:147]
	v_pk_add_f32 v[148:149], v[186:187], v[188:189]
	v_pk_add_f32 v[174:175], v[190:191], v[192:193]
	v_mul_f32_e32 v195, v32, v32
	v_mul_f32_e32 v197, v33, v33
	v_mul_f32_e32 v201, v34, v34
	v_mul_f32_e32 v203, v35, v35
	v_pk_add_f32 v[148:149], v[148:149], v[174:175]
	v_mov_b32_e32 v194, v32
	v_mov_b32_e32 v196, v33
	v_mov_b32_e32 v200, v34
	v_mov_b32_e32 v202, v35
	v_pk_add_f32 v[146:147], v[146:147], v[148:149]
	v_pk_add_f32 v[148:149], v[194:195], v[196:197]
	v_pk_add_f32 v[174:175], v[200:201], v[202:203]
	s_nop 0
	v_pk_add_f32 v[148:149], v[148:149], v[174:175]
	s_nop 0
	v_pk_add_f32 v[146:147], v[146:147], v[148:149]
	v_mov_b32_e32 v148, v146
	v_mov_b32_e32 v149, v147
	s_nop 1
	v_permlane16_swap_b32_e32 v146, v148
	v_permlane16_swap_b32_e32 v147, v149
	v_pk_add_f32 v[146:147], v[146:147], v[148:149]
	v_mov_b32_e32 v148, v146
	v_mov_b32_e32 v149, v147
	s_nop 1
	v_permlane32_swap_b32_e32 v146, v148
	v_permlane32_swap_b32_e32 v147, v149
	s_and_saveexec_b64 s[40:41], s[36:37]
	s_cbranch_execz .LBB0_381
	v_pk_add_f32 v[146:147], v[146:147], v[148:149]
	ds_write_b64 v171, v[146:147] offset:4608
.LBB0_381:
	s_or_b64 exec, exec, s[40:41]
	v_mul_f32_e32 v175, v28, v28
	v_mul_f32_e32 v174, v26, v26
	v_add_f32_e32 v146, v28, v29
	s_waitcnt lgkmcnt(0)
	v_add_f32_e32 v148, v30, v31
	v_mul_f32_e32 v179, v29, v29
	v_mul_f32_e32 v181, v30, v30
	v_mul_f32_e32 v183, v31, v31
	v_mul_f32_e32 v147, v24, v24
	v_mul_f32_e32 v149, v25, v25
	v_pk_fma_f32 v[184:185], v[26:27], v[26:27], v[174:175] op_sel_hi:[1,1,0]
	v_mov_b32_e32 v174, v24
	v_mov_b32_e32 v178, v25
	v_mov_b32_e32 v180, v26
	v_mov_b32_e32 v182, v27
	v_pk_add_f32 v[174:175], v[174:175], v[178:179]
	v_pk_add_f32 v[178:179], v[180:181], v[182:183]
	v_pk_add_f32 v[146:147], v[146:147], v[148:149]
	v_mov_b32_e32 v184, v177
	v_mul_f32_e32 v187, v20, v20
	v_mul_f32_e32 v189, v21, v21
	v_mul_f32_e32 v191, v22, v22
	v_mul_f32_e32 v193, v23, v23
	v_pk_add_f32 v[174:175], v[174:175], v[178:179]
	v_pk_add_f32 v[146:147], v[146:147], v[184:185]
	v_mov_b32_e32 v186, v20
	v_mov_b32_e32 v188, v21
	v_mov_b32_e32 v190, v22
	v_mov_b32_e32 v192, v23
	v_pk_add_f32 v[146:147], v[174:175], v[146:147]
	v_pk_add_f32 v[148:149], v[186:187], v[188:189]
	v_pk_add_f32 v[174:175], v[190:191], v[192:193]
	v_mul_f32_e32 v195, v16, v16
	v_mul_f32_e32 v197, v17, v17
	v_mul_f32_e32 v201, v18, v18
	v_mul_f32_e32 v203, v19, v19
	v_pk_add_f32 v[148:149], v[148:149], v[174:175]
	v_mov_b32_e32 v194, v16
	v_mov_b32_e32 v196, v17
	v_mov_b32_e32 v200, v18
	v_mov_b32_e32 v202, v19
	v_pk_add_f32 v[146:147], v[146:147], v[148:149]
	v_pk_add_f32 v[148:149], v[194:195], v[196:197]
	v_pk_add_f32 v[174:175], v[200:201], v[202:203]
	s_nop 0
	v_pk_add_f32 v[148:149], v[148:149], v[174:175]
	s_nop 0
	v_pk_add_f32 v[146:147], v[146:147], v[148:149]
	v_mov_b32_e32 v148, v146
	v_mov_b32_e32 v149, v147
	s_nop 1
	v_permlane16_swap_b32_e32 v146, v148
	v_permlane16_swap_b32_e32 v147, v149
	v_pk_add_f32 v[146:147], v[146:147], v[148:149]
	v_mov_b32_e32 v148, v146
	v_mov_b32_e32 v149, v147
	s_nop 1
	v_permlane32_swap_b32_e32 v146, v148
	v_permlane32_swap_b32_e32 v147, v149
	s_and_saveexec_b64 s[40:41], s[36:37]
	s_cbranch_execz .LBB0_383
	v_pk_add_f32 v[146:147], v[146:147], v[148:149]
	ds_write_b64 v171, v[146:147] offset:5120
.LBB0_383:
	s_or_b64 exec, exec, s[40:41]
	v_mul_f32_e32 v175, v12, v12
	v_mul_f32_e32 v174, v10, v10
	v_add_f32_e32 v146, v12, v13
	s_waitcnt lgkmcnt(0)
	v_add_f32_e32 v148, v14, v15
	v_mul_f32_e32 v179, v13, v13
	v_mul_f32_e32 v181, v14, v14
	v_mul_f32_e32 v183, v15, v15
	v_mul_f32_e32 v147, v8, v8
	v_mul_f32_e32 v149, v9, v9
	v_pk_fma_f32 v[184:185], v[10:11], v[10:11], v[174:175] op_sel_hi:[1,1,0]
	v_mov_b32_e32 v174, v8
	v_mov_b32_e32 v178, v9
	v_mov_b32_e32 v180, v10
	v_mov_b32_e32 v182, v11
	v_pk_add_f32 v[174:175], v[174:175], v[178:179]
	v_pk_add_f32 v[178:179], v[180:181], v[182:183]
	v_pk_add_f32 v[146:147], v[146:147], v[148:149]
	v_mov_b32_e32 v184, v177
	v_mul_f32_e32 v187, v4, v4
	v_mul_f32_e32 v189, v5, v5
	v_mul_f32_e32 v191, v6, v6
	v_mul_f32_e32 v193, v7, v7
	v_pk_add_f32 v[174:175], v[174:175], v[178:179]
	v_pk_add_f32 v[146:147], v[146:147], v[184:185]
	v_mov_b32_e32 v186, v4
	v_mov_b32_e32 v188, v5
	v_mov_b32_e32 v190, v6
	v_mov_b32_e32 v192, v7
	v_pk_add_f32 v[146:147], v[174:175], v[146:147]
	v_pk_add_f32 v[148:149], v[186:187], v[188:189]
	v_pk_add_f32 v[174:175], v[190:191], v[192:193]
	v_mul_f32_e32 v195, v0, v0
	v_mul_f32_e32 v197, v1, v1
	v_mul_f32_e32 v201, v2, v2
	v_mul_f32_e32 v203, v3, v3
	v_pk_add_f32 v[148:149], v[148:149], v[174:175]
	v_mov_b32_e32 v194, v0
	v_mov_b32_e32 v196, v1
	v_mov_b32_e32 v200, v2
	v_mov_b32_e32 v202, v3
	v_pk_add_f32 v[146:147], v[146:147], v[148:149]
	v_pk_add_f32 v[148:149], v[194:195], v[196:197]
	v_pk_add_f32 v[174:175], v[200:201], v[202:203]
	s_nop 0
	v_pk_add_f32 v[148:149], v[148:149], v[174:175]
	s_nop 0
	v_pk_add_f32 v[146:147], v[146:147], v[148:149]
	v_mov_b32_e32 v148, v146
	v_mov_b32_e32 v149, v147
	s_nop 1
	v_permlane16_swap_b32_e32 v146, v148
	v_permlane16_swap_b32_e32 v147, v149
	v_pk_add_f32 v[146:147], v[146:147], v[148:149]
	v_mov_b32_e32 v148, v146
	v_mov_b32_e32 v149, v147
	s_nop 1
	v_permlane32_swap_b32_e32 v146, v148
	v_permlane32_swap_b32_e32 v147, v149
	s_and_saveexec_b64 s[40:41], s[36:37]
	s_cbranch_execz .LBB0_385
	v_pk_add_f32 v[146:147], v[146:147], v[148:149]
	ds_write_b64 v171, v[146:147] offset:5632

;     __device__ __forceinline__ void operator()(f32x4 (&acc)[2][2][4][2], const Unit& u, int wr, int wc, int fr, int fq, LAS unsigned char* lds) const {
;     ...
;             for (int m = 0; m < 4; ++m) { float sv = 0.f, qv = 0.f;
; #pragma unroll
;                 for (int bj = 0; bj < 2; ++bj)
; #pragma unroll
;                     for (int n = 0; n < 2; ++n) { const f32x4 x = acc[ai][bj][m][n]; sv += (x[0] + x[1]) + (x[2] + x[3]); qv += (x[0] * x[0] + x[1] * x[1]) + (x[2] * x[2] + x[3] * x[3]); }
;                 sv += __shfl_xor(sv, 16); sv += __shfl_xor(sv, 32); qv += __shfl_xor(qv, 16); qv += __shfl_xor(qv, 32);
;                 if (fq == 0) P[(ai * HALF + wr * 64 + m * 16 + fr) * 4 + wc] = (f32x2){sv, qv};
;                 __builtin_amdgcn_sched_barrier(0); }
;     ...
;                     for (int n = 0; n < 2; ++n) { const f32x4 gn = *(const f32x4*)(gain + col0 + bj * HALF + n * 16), bs = *(const f32x4*)(bias + col0 + bj * HALF + n * 16);
.LBB0_477:
	global_load_dwordx4 v[210:213], v[132:133], off
	global_load_dwordx4 v[214:217], v[132:133], off offset:64
	global_load_dwordx4 v[218:221], v[132:133], off offset:512
	global_load_dwordx4 v[222:225], v[132:133], off offset:576
	global_load_dwordx4 v[226:229], v[134:135], off
	global_load_dwordx4 v[230:233], v[134:135], off offset:64
	global_load_dwordx4 v[234:237], v[134:135], off offset:512
	global_load_dwordx4 v[238:241], v[134:135], off offset:576
	v_and_b32_e32 v157, 64, v198
	v_xor_b32_e32 v156, 16, v198
	v_add_u32_e32 v181, 64, v157
	v_cmp_lt_i32_e32 vcc, v156, v181
	v_mul_f32_e32 v160, v122, v122
	v_add_f32_e32 v158, v126, v127
	v_cndmask_b32_e32 v156, v198, v156, vcc
	v_lshlrev_b32_e32 v161, 2, v156
	v_add_f32_e32 v156, v124, v125
	v_mul_f32_e32 v183, v124, v124
	v_mul_f32_e32 v185, v125, v125
	v_mul_f32_e32 v187, v126, v126
	v_mul_f32_e32 v189, v127, v127
	v_mul_f32_e32 v157, v120, v120
	v_mul_f32_e32 v159, v121, v121
	v_pk_fma_f32 v[190:191], v[122:123], v[122:123], v[160:161] op_sel_hi:[1,1,0]
	v_mov_b32_e32 v182, v120
	v_mov_b32_e32 v184, v121
	v_mov_b32_e32 v186, v122
	v_mov_b32_e32 v188, v123
	v_pk_add_f32 v[182:183], v[182:183], v[184:185]
	v_pk_add_f32 v[184:185], v[186:187], v[188:189]
	v_pk_add_f32 v[156:157], v[156:157], v[158:159]
	v_mov_b32_e32 v190, v177
	v_mul_f32_e32 v193, v116, v116
	v_mul_f32_e32 v195, v117, v117
	v_mul_f32_e32 v197, v118, v118
	v_mul_f32_e32 v201, v119, v119
	v_pk_add_f32 v[182:183], v[182:183], v[184:185]
	v_pk_add_f32 v[156:157], v[156:157], v[190:191]
	v_mov_b32_e32 v192, v116
	v_mov_b32_e32 v194, v117
	v_mov_b32_e32 v196, v118
	v_mov_b32_e32 v200, v119
	v_pk_add_f32 v[156:157], v[182:183], v[156:157]
	v_pk_add_f32 v[158:159], v[192:193], v[194:195]
	v_pk_add_f32 v[182:183], v[196:197], v[200:201]
	v_mul_f32_e32 v203, v112, v112
	v_mul_f32_e32 v205, v113, v113
	v_mul_f32_e32 v207, v114, v114
	v_mul_f32_e32 v209, v115, v115
	v_pk_add_f32 v[158:159], v[158:159], v[182:183]
	v_mov_b32_e32 v202, v112
	v_mov_b32_e32 v204, v113
	v_mov_b32_e32 v206, v114
	v_mov_b32_e32 v208, v115
	v_pk_add_f32 v[156:157], v[156:157], v[158:159]
	v_pk_add_f32 v[158:159], v[202:203], v[204:205]
	v_pk_add_f32 v[182:183], v[206:207], v[208:209]
	v_xor_b32_e32 v160, 32, v198
	v_pk_add_f32 v[158:159], v[158:159], v[182:183]
	v_cmp_lt_i32_e32 vcc, v160, v181
	v_pk_add_f32 v[156:157], v[156:157], v[158:159]
	v_mov_b32_e32 v158, v156
	v_mov_b32_e32 v159, v157
	s_nop 1
	v_permlane16_swap_b32_e32 v156, v158
	v_permlane16_swap_b32_e32 v157, v159
	v_cndmask_b32_e32 v160, v198, v160, vcc
	v_lshlrev_b32_e32 v181, 2, v160
	v_mov_b32_e32 v160, v252
	v_pk_add_f32 v[156:157], v[156:157], v[158:159]
	v_mov_b32_e32 v158, v156
	v_mov_b32_e32 v159, v157
	s_nop 1
	v_permlane32_swap_b32_e32 v156, v158
	v_permlane32_swap_b32_e32 v157, v159
	v_readfirstlane_b32 s19, v160
	s_and_saveexec_b64 s[38:39], s[36:37]
	s_cbranch_execz .LBB0_479
	v_pk_add_f32 v[156:157], v[156:157], v[158:159]
	ds_write_b64 v180, v[156:157]
.LBB0_479:
	s_or_b64 exec, exec, s[38:39]
	v_mul_f32_e32 v183, v108, v108
	v_mul_f32_e32 v182, v106, v106
	v_add_f32_e32 v156, v108, v109
	s_waitcnt lgkmcnt(0)
	v_add_f32_e32 v158, v110, v111
	v_mul_f32_e32 v185, v109, v109
	v_mul_f32_e32 v187, v110, v110
	v_mul_f32_e32 v189, v111, v111
	v_mul_f32_e32 v157, v104, v104
	v_mul_f32_e32 v159, v105, v105
	v_pk_fma_f32 v[190:191], v[106:107], v[106:107], v[182:183] op_sel_hi:[1,1,0]
	v_mov_b32_e32 v182, v104
	v_mov_b32_e32 v184, v105
	v_mov_b32_e32 v186, v106
	v_mov_b32_e32 v188, v107
	v_pk_add_f32 v[182:183], v[182:183], v[184:185]
	v_pk_add_f32 v[184:185], v[186:187], v[188:189]
	v_pk_add_f32 v[156:157], v[156:157], v[158:159]
	v_mov_b32_e32 v190, v177
	v_mul_f32_e32 v193, v100, v100
	v_mul_f32_e32 v195, v101, v101
	v_mul_f32_e32 v197, v102, v102
	v_mul_f32_e32 v201, v103, v103
	v_pk_add_f32 v[182:183], v[182:183], v[184:185]
	v_pk_add_f32 v[156:157], v[156:157], v[190:191]
	v_mov_b32_e32 v192, v100
	v_mov_b32_e32 v194, v101
	v_mov_b32_e32 v196, v102
	v_mov_b32_e32 v200, v103
	v_pk_add_f32 v[156:157], v[182:183], v[156:157]
	v_pk_add_f32 v[158:159], v[192:193], v[194:195]
	v_pk_add_f32 v[182:183], v[196:197], v[200:201]
	v_mul_f32_e32 v203, v96, v96
	v_mul_f32_e32 v205, v97, v97
	v_mul_f32_e32 v207, v98, v98
	v_mul_f32_e32 v209, v99, v99
	v_pk_add_f32 v[158:159], v[158:159], v[182:183]
	v_mov_b32_e32 v202, v96
	v_mov_b32_e32 v204, v97
	v_mov_b32_e32 v206, v98
	v_mov_b32_e32 v208, v99
	v_pk_add_f32 v[156:157], v[156:157], v[158:159]
	v_pk_add_f32 v[158:159], v[202:203], v[204:205]
	v_pk_add_f32 v[182:183], v[206:207], v[208:209]
	s_nop 0
	v_pk_add_f32 v[158:159], v[158:159], v[182:183]
	s_nop 0
	v_pk_add_f32 v[156:157], v[156:157], v[158:159]
	v_mov_b32_e32 v158, v156
	v_mov_b32_e32 v159, v157
	s_nop 1
	v_permlane16_swap_b32_e32 v156, v158
	v_permlane16_swap_b32_e32 v157, v159
	v_pk_add_f32 v[156:157], v[156:157], v[158:159]
	v_mov_b32_e32 v158, v156
	v_mov_b32_e32 v159, v157
	s_nop 1
	v_permlane32_swap_b32_e32 v156, v158
	v_permlane32_swap_b32_e32 v157, v159
	s_and_saveexec_b64 s[38:39], s[36:37]
	s_cbranch_execz .LBB0_481
	v_pk_add_f32 v[156:157], v[156:157], v[158:159]
	ds_write_b64 v180, v[156:157] offset:512
;     __device__ __forceinline__ void operator()(f32x4 (&acc)[2][2][4][2], const Unit& u, int wr, int wc, int fr, int fq, LAS unsigned char* lds) const {
;     ...
;             for (int m = 0; m < 4; ++m) { float sv = 0.f, qv = 0.f;
; #pragma unroll
;                 for (int bj = 0; bj < 2; ++bj)
; #pragma unroll
;                     for (int n = 0; n < 2; ++n) { const f32x4 x = acc[ai][bj][m][n]; sv += (x[0] + x[1]) + (x[2] + x[3]); qv += (x[0] * x[0] + x[1] * x[1]) + (x[2] * x[2] + x[3] * x[3]); }
;                 sv += __shfl_xor(sv, 16); sv += __shfl_xor(sv, 32); qv += __shfl_xor(qv, 16); qv += __shfl_xor(qv, 32);
;                 if (fq == 0) P[(ai * HALF + wr * 64 + m * 16 + fr) * 4 + wc] = (f32x2){sv, qv};
;                 __builtin_amdgcn_sched_barrier(0); }
.LBB0_481:
	s_or_b64 exec, exec, s[38:39]
	v_mul_f32_e32 v183, v92, v92
	v_mul_f32_e32 v182, v90, v90
	v_add_f32_e32 v156, v92, v93
	s_waitcnt lgkmcnt(0)
	v_add_f32_e32 v158, v94, v95
	v_mul_f32_e32 v185, v93, v93
	v_mul_f32_e32 v187, v94, v94
	v_mul_f32_e32 v189, v95, v95
	v_mul_f32_e32 v157, v88, v88
	v_mul_f32_e32 v159, v89, v89
	v_pk_fma_f32 v[190:191], v[90:91], v[90:91], v[182:183] op_sel_hi:[1,1,0]
	v_mov_b32_e32 v182, v88
	v_mov_b32_e32 v184, v89
	v_mov_b32_e32 v186, v90
	v_mov_b32_e32 v188, v91
	v_pk_add_f32 v[182:183], v[182:183], v[184:185]
	v_pk_add_f32 v[184:185], v[186:187], v[188:189]
	v_pk_add_f32 v[156:157], v[156:157], v[158:159]
	v_mov_b32_e32 v190, v177
	v_mul_f32_e32 v193, v84, v84
	v_mul_f32_e32 v195, v85, v85
	v_mul_f32_e32 v197, v86, v86
	v_mul_f32_e32 v201, v87, v87
	v_pk_add_f32 v[182:183], v[182:183], v[184:185]
	v_pk_add_f32 v[156:157], v[156:157], v[190:191]
	v_mov_b32_e32 v192, v84
	v_mov_b32_e32 v194, v85
	v_mov_b32_e32 v196, v86
	v_mov_b32_e32 v200, v87
	v_pk_add_f32 v[156:157], v[182:183], v[156:157]
	v_pk_add_f32 v[158:159], v[192:193], v[194:195]
	v_pk_add_f32 v[182:183], v[196:197], v[200:201]
	v_mul_f32_e32 v203, v80, v80
	v_mul_f32_e32 v205, v81, v81
	v_mul_f32_e32 v207, v82, v82
	v_mul_f32_e32 v209, v83, v83
	v_pk_add_f32 v[158:159], v[158:159], v[182:183]
	v_mov_b32_e32 v202, v80
	v_mov_b32_e32 v204, v81
	v_mov_b32_e32 v206, v82
	v_mov_b32_e32 v208, v83
	v_pk_add_f32 v[156:157], v[156:157], v[158:159]
	v_pk_add_f32 v[158:159], v[202:203], v[204:205]
	v_pk_add_f32 v[182:183], v[206:207], v[208:209]
	s_nop 0
	v_pk_add_f32 v[158:159], v[158:159], v[182:183]
	s_nop 0
	v_pk_add_f32 v[156:157], v[156:157], v[158:159]
	v_mov_b32_e32 v158, v156
	v_mov_b32_e32 v159, v157
	s_nop 1
	v_permlane16_swap_b32_e32 v156, v158
	v_permlane16_swap_b32_e32 v157, v159
	v_pk_add_f32 v[156:157], v[156:157], v[158:159]
	v_mov_b32_e32 v158, v156
	v_mov_b32_e32 v159, v157
	s_nop 1
	v_permlane32_swap_b32_e32 v156, v158
	v_permlane32_swap_b32_e32 v157, v159
	s_mov_b64 s[38:39], exec
	s_and_b64 s[20:21], s[38:39], s[36:37]
	v_mov_b32_e32 v244, v199
	s_mov_b64 exec, s[20:21]
	s_cbranch_execz .LBB0_483
	v_pk_add_f32 v[156:157], v[156:157], v[158:159]
	ds_write_b64 v180, v[156:157] offset:1024
.LBB0_483:
	s_or_b64 exec, exec, s[38:39]
	v_mul_f32_e32 v183, v76, v76
	v_mul_f32_e32 v182, v74, v74
	v_add_f32_e32 v156, v76, v77
	s_waitcnt lgkmcnt(0)
	v_add_f32_e32 v158, v78, v79
	v_mul_f32_e32 v185, v77, v77
	v_mul_f32_e32 v187, v78, v78
	v_mul_f32_e32 v189, v79, v79
	v_mul_f32_e32 v157, v72, v72
	v_mul_f32_e32 v159, v73, v73
	v_pk_fma_f32 v[190:191], v[74:75], v[74:75], v[182:183] op_sel_hi:[1,1,0]
	v_mov_b32_e32 v182, v72
	v_mov_b32_e32 v184, v73
	v_mov_b32_e32 v186, v74
	v_mov_b32_e32 v188, v75
	v_pk_add_f32 v[182:183], v[182:183], v[184:185]
	v_pk_add_f32 v[184:185], v[186:187], v[188:189]
	v_pk_add_f32 v[156:157], v[156:157], v[158:159]
	v_mov_b32_e32 v190, v177
	v_mul_f32_e32 v193, v68, v68
	v_mul_f32_e32 v195, v69, v69
	v_mul_f32_e32 v197, v70, v70
	v_mul_f32_e32 v201, v71, v71
	v_pk_add_f32 v[182:183], v[182:183], v[184:185]
	v_pk_add_f32 v[156:157], v[156:157], v[190:191]
	v_mov_b32_e32 v192, v68
	v_mov_b32_e32 v194, v69
	v_mov_b32_e32 v196, v70
	v_mov_b32_e32 v200, v71
	v_pk_add_f32 v[156:157], v[182:183], v[156:157]
	v_pk_add_f32 v[158:159], v[192:193], v[194:195]
	v_pk_add_f32 v[182:183], v[196:197], v[200:201]
	v_mul_f32_e32 v203, v64, v64
	v_mul_f32_e32 v205, v65, v65
	v_mul_f32_e32 v207, v66, v66
	v_mul_f32_e32 v209, v67, v67
	v_pk_add_f32 v[158:159], v[158:159], v[182:183]
	v_mov_b32_e32 v202, v64
	v_mov_b32_e32 v204, v65
	v_mov_b32_e32 v206, v66
	v_mov_b32_e32 v208, v67
	v_pk_add_f32 v[156:157], v[156:157], v[158:159]
	v_pk_add_f32 v[158:159], v[202:203], v[204:205]
	v_pk_add_f32 v[182:183], v[206:207], v[208:209]
	s_nop 0
	v_pk_add_f32 v[158:159], v[158:159], v[182:183]
	s_nop 0
	v_pk_add_f32 v[156:157], v[156:157], v[158:159]
	v_mov_b32_e32 v158, v156
	v_mov_b32_e32 v159, v157
	s_nop 1
	v_permlane16_swap_b32_e32 v156, v158
	v_permlane16_swap_b32_e32 v157, v159
	v_pk_add_f32 v[156:157], v[156:157], v[158:159]
	v_mov_b32_e32 v158, v156
	v_mov_b32_e32 v159, v157
	s_nop 1
	v_permlane32_swap_b32_e32 v156, v158
	v_permlane32_swap_b32_e32 v157, v159
	s_and_saveexec_b64 s[38:39], s[36:37]
	s_cbranch_execz .LBB0_485
	v_pk_add_f32 v[156:157], v[156:157], v[158:159]
	ds_write_b64 v180, v[156:157] offset:1536
.LBB0_485:
	s_or_b64 exec, exec, s[38:39]
	v_mul_f32_e32 v183, v60, v60
	v_mul_f32_e32 v182, v58, v58
	v_add_f32_e32 v156, v60, v61
	s_waitcnt lgkmcnt(0)
	v_add_f32_e32 v158, v62, v63
	v_mul_f32_e32 v185, v61, v61
	v_mul_f32_e32 v187, v62, v62
	v_mul_f32_e32 v189, v63, v63
	v_mul_f32_e32 v157, v56, v56
	v_mul_f32_e32 v159, v57, v57
	v_pk_fma_f32 v[190:191], v[58:59], v[58:59], v[182:183] op_sel_hi:[1,1,0]
	v_mov_b32_e32 v182, v56
	v_mov_b32_e32 v184, v57
	v_mov_b32_e32 v186, v58
	v_mov_b32_e32 v188, v59
	v_pk_add_f32 v[182:183], v[182:183], v[184:185]
	v_pk_add_f32 v[184:185], v[186:187], v[188:189]
	v_pk_add_f32 v[156:157], v[156:157], v[158:159]
	v_mov_b32_e32 v190, v177
	v_mul_f32_e32 v193, v52, v52
	v_mul_f32_e32 v195, v53, v53
	v_mul_f32_e32 v197, v54, v54
	v_mul_f32_e32 v201, v55, v55
	v_pk_add_f32 v[182:183], v[182:183], v[184:185]
	v_pk_add_f32 v[156:157], v[156:157], v[190:191]
	v_mov_b32_e32 v192, v52
	v_mov_b32_e32 v194, v53
	v_mov_b32_e32 v196, v54
	v_mov_b32_e32 v200, v55
	v_pk_add_f32 v[156:157], v[182:183], v[156:157]
	v_pk_add_f32 v[158:159], v[192:193], v[194:195]
	v_pk_add_f32 v[182:183], v[196:197], v[200:201]
	v_mul_f32_e32 v203, v48, v48
	v_mul_f32_e32 v205, v49, v49
	v_mul_f32_e32 v207, v50, v50
	v_mul_f32_e32 v209, v51, v51
	v_pk_add_f32 v[158:159], v[158:159], v[182:183]
	v_mov_b32_e32 v202, v48
	v_mov_b32_e32 v204, v49
	v_mov_b32_e32 v206, v50
	v_mov_b32_e32 v208, v51
	v_pk_add_f32 v[156:157], v[156:157], v[158:159]
	v_pk_add_f32 v[158:159], v[202:203], v[204:205]
	v_pk_add_f32 v[182:183], v[206:207], v[208:209]
	s_nop 0
	v_pk_add_f32 v[158:159], v[158:159], v[182:183]
	s_nop 0
	v_pk_add_f32 v[156:157], v[156:157], v[158:159]
	v_mov_b32_e32 v158, v156
	v_mov_b32_e32 v159, v157
	s_nop 1
	v_permlane16_swap_b32_e32 v156, v158
	v_permlane16_swap_b32_e32 v157, v159
	v_pk_add_f32 v[156:157], v[156:157], v[158:159]
	v_mov_b32_e32 v158, v156
	v_mov_b32_e32 v159, v157
	s_nop 1
	v_permlane32_swap_b32_e32 v156, v158
	v_permlane32_swap_b32_e32 v157, v159
	s_and_saveexec_b64 s[38:39], s[36:37]
	s_cbranch_execz .LBB0_487
	v_pk_add_f32 v[156:157], v[156:157], v[158:159]
	ds_write_b64 v180, v[156:157] offset:4096
;     __device__ __forceinline__ void operator()(f32x4 (&acc)[2][2][4][2], const Unit& u, int wr, int wc, int fr, int fq, LAS unsigned char* lds) const {
;     ...
;             for (int m = 0; m < 4; ++m) { float sv = 0.f, qv = 0.f;
; #pragma unroll
;                 for (int bj = 0; bj < 2; ++bj)
; #pragma unroll
;                     for (int n = 0; n < 2; ++n) { const f32x4 x = acc[ai][bj][m][n]; sv += (x[0] + x[1]) + (x[2] + x[3]); qv += (x[0] * x[0] + x[1] * x[1]) + (x[2] * x[2] + x[3] * x[3]); }
;                 sv += __shfl_xor(sv, 16); sv += __shfl_xor(sv, 32); qv += __shfl_xor(qv, 16); qv += __shfl_xor(qv, 32);
;                 if (fq == 0) P[(ai * HALF + wr * 64 + m * 16 + fr) * 4 + wc] = (f32x2){sv, qv};
;                 __builtin_amdgcn_sched_barrier(0); }
.LBB0_487:
	s_or_b64 exec, exec, s[38:39]
	v_mul_f32_e32 v183, v44, v44
	v_mul_f32_e32 v182, v42, v42
	v_add_f32_e32 v156, v44, v45
	s_waitcnt lgkmcnt(0)
	v_add_f32_e32 v158, v46, v47
	v_mul_f32_e32 v185, v45, v45
	v_mul_f32_e32 v187, v46, v46
	v_mul_f32_e32 v189, v47, v47
	v_mul_f32_e32 v157, v40, v40
	v_mul_f32_e32 v159, v41, v41
	v_pk_fma_f32 v[190:191], v[42:43], v[42:43], v[182:183] op_sel_hi:[1,1,0]
	v_mov_b32_e32 v182, v40
	v_mov_b32_e32 v184, v41
	v_mov_b32_e32 v186, v42
	v_mov_b32_e32 v188, v43
	v_pk_add_f32 v[182:183], v[182:183], v[184:185]
	v_pk_add_f32 v[184:185], v[186:187], v[188:189]
	v_pk_add_f32 v[156:157], v[156:157], v[158:159]
	v_mov_b32_e32 v190, v177
	v_mul_f32_e32 v193, v36, v36
	v_mul_f32_e32 v195, v37, v37
	v_mul_f32_e32 v197, v38, v38
	v_mul_f32_e32 v201, v39, v39
	v_pk_add_f32 v[182:183], v[182:183], v[184:185]
	v_pk_add_f32 v[156:157], v[156:157], v[190:191]
	v_mov_b32_e32 v192, v36
	v_mov_b32_e32 v194, v37
	v_mov_b32_e32 v196, v38
	v_mov_b32_e32 v200, v39
	v_pk_add_f32 v[156:157], v[182:183], v[156:157]
	v_pk_add_f32 v[158:159], v[192:193], v[194:195]
	v_pk_add_f32 v[182:183], v[196:197], v[200:201]
	v_mul_f32_e32 v203, v32, v32
	v_mul_f32_e32 v205, v33, v33
	v_mul_f32_e32 v207, v34, v34
	v_mul_f32_e32 v209, v35, v35
	v_pk_add_f32 v[158:159], v[158:159], v[182:183]
	v_mov_b32_e32 v202, v32
	v_mov_b32_e32 v204, v33
	v_mov_b32_e32 v206, v34
	v_mov_b32_e32 v208, v35
	v_pk_add_f32 v[156:157], v[156:157], v[158:159]
	v_pk_add_f32 v[158:159], v[202:203], v[204:205]
	v_pk_add_f32 v[182:183], v[206:207], v[208:209]
	s_nop 0
	v_pk_add_f32 v[158:159], v[158:159], v[182:183]
	s_nop 0
	v_pk_add_f32 v[156:157], v[156:157], v[158:159]
	v_mov_b32_e32 v158, v156
	v_mov_b32_e32 v159, v157
	s_nop 1
	v_permlane16_swap_b32_e32 v156, v158
	v_permlane16_swap_b32_e32 v157, v159
	v_pk_add_f32 v[156:157], v[156:157], v[158:159]
	v_mov_b32_e32 v158, v156
	v_mov_b32_e32 v159, v157
	s_nop 1
	v_permlane32_swap_b32_e32 v156, v158
	v_permlane32_swap_b32_e32 v157, v159
	s_and_saveexec_b64 s[38:39], s[36:37]
	s_cbranch_execz .LBB0_489
	v_pk_add_f32 v[156:157], v[156:157], v[158:159]
	ds_write_b64 v180, v[156:157] offset:4608
.LBB0_489:
	s_or_b64 exec, exec, s[38:39]
	v_mul_f32_e32 v183, v28, v28
	v_mul_f32_e32 v182, v26, v26
	v_add_f32_e32 v156, v28, v29
	s_waitcnt lgkmcnt(0)
	v_add_f32_e32 v158, v30, v31
	v_mul_f32_e32 v185, v29, v29
	v_mul_f32_e32 v187, v30, v30
	v_mul_f32_e32 v189, v31, v31
	v_mul_f32_e32 v157, v24, v24
	v_mul_f32_e32 v159, v25, v25
	v_pk_fma_f32 v[190:191], v[26:27], v[26:27], v[182:183] op_sel_hi:[1,1,0]
	v_mov_b32_e32 v182, v24
	v_mov_b32_e32 v184, v25
	v_mov_b32_e32 v186, v26
	v_mov_b32_e32 v188, v27
	v_pk_add_f32 v[182:183], v[182:183], v[184:185]
	v_pk_add_f32 v[184:185], v[186:187], v[188:189]
	v_pk_add_f32 v[156:157], v[156:157], v[158:159]
	v_mov_b32_e32 v190, v177
	v_mul_f32_e32 v193, v20, v20
	v_mul_f32_e32 v195, v21, v21
	v_mul_f32_e32 v197, v22, v22
	v_mul_f32_e32 v201, v23, v23
	v_pk_add_f32 v[182:183], v[182:183], v[184:185]
	v_pk_add_f32 v[156:157], v[156:157], v[190:191]
	v_mov_b32_e32 v192, v20
	v_mov_b32_e32 v194, v21
	v_mov_b32_e32 v196, v22
	v_mov_b32_e32 v200, v23
	v_pk_add_f32 v[156:157], v[182:183], v[156:157]
	v_pk_add_f32 v[158:159], v[192:193], v[194:195]
	v_pk_add_f32 v[182:183], v[196:197], v[200:201]
	v_mul_f32_e32 v203, v16, v16
	v_mul_f32_e32 v205, v17, v17
	v_mul_f32_e32 v207, v18, v18
	v_mul_f32_e32 v209, v19, v19
	v_pk_add_f32 v[158:159], v[158:159], v[182:183]
	v_mov_b32_e32 v202, v16
	v_mov_b32_e32 v204, v17
	v_mov_b32_e32 v206, v18
	v_mov_b32_e32 v208, v19
	v_pk_add_f32 v[156:157], v[156:157], v[158:159]
	v_pk_add_f32 v[158:159], v[202:203], v[204:205]
	v_pk_add_f32 v[182:183], v[206:207], v[208:209]
	s_nop 0
	v_pk_add_f32 v[158:159], v[158:159], v[182:183]
	s_nop 0
	v_pk_add_f32 v[156:157], v[156:157], v[158:159]
	v_mov_b32_e32 v158, v156
	v_mov_b32_e32 v159, v157
	s_nop 1
	v_permlane16_swap_b32_e32 v156, v158
	v_permlane16_swap_b32_e32 v157, v159
	v_pk_add_f32 v[156:157], v[156:157], v[158:159]
	v_mov_b32_e32 v158, v156
	v_mov_b32_e32 v159, v157
	s_nop 1
	v_permlane32_swap_b32_e32 v156, v158
	v_permlane32_swap_b32_e32 v157, v159
	s_and_saveexec_b64 s[38:39], s[36:37]
	s_cbranch_execz .LBB0_491
	v_pk_add_f32 v[156:157], v[156:157], v[158:159]
	ds_write_b64 v180, v[156:157] offset:5120
.LBB0_491:
	s_or_b64 exec, exec, s[38:39]
	v_mul_f32_e32 v183, v12, v12
	v_mul_f32_e32 v182, v10, v10
	v_add_f32_e32 v156, v12, v13
	s_waitcnt lgkmcnt(0)
	v_add_f32_e32 v158, v14, v15
	v_mul_f32_e32 v185, v13, v13
	v_mul_f32_e32 v187, v14, v14
	v_mul_f32_e32 v189, v15, v15
	v_mul_f32_e32 v157, v8, v8
	v_mul_f32_e32 v159, v9, v9
	v_pk_fma_f32 v[190:191], v[10:11], v[10:11], v[182:183] op_sel_hi:[1,1,0]
	v_mov_b32_e32 v182, v8
	v_mov_b32_e32 v184, v9
	v_mov_b32_e32 v186, v10
	v_mov_b32_e32 v188, v11
	v_pk_add_f32 v[182:183], v[182:183], v[184:185]
	v_pk_add_f32 v[184:185], v[186:187], v[188:189]
	v_pk_add_f32 v[156:157], v[156:157], v[158:159]
	v_mov_b32_e32 v190, v177
	v_mul_f32_e32 v193, v4, v4
	v_mul_f32_e32 v195, v5, v5
	v_mul_f32_e32 v197, v6, v6
	v_mul_f32_e32 v201, v7, v7
	v_pk_add_f32 v[182:183], v[182:183], v[184:185]
	v_pk_add_f32 v[156:157], v[156:157], v[190:191]
	v_mov_b32_e32 v192, v4
	v_mov_b32_e32 v194, v5
	v_mov_b32_e32 v196, v6
	v_mov_b32_e32 v200, v7
	v_pk_add_f32 v[156:157], v[182:183], v[156:157]
	v_pk_add_f32 v[158:159], v[192:193], v[194:195]
	v_pk_add_f32 v[182:183], v[196:197], v[200:201]
	v_mul_f32_e32 v203, v0, v0
	v_mul_f32_e32 v205, v1, v1
	v_mul_f32_e32 v207, v2, v2
	v_mul_f32_e32 v209, v3, v3
	v_pk_add_f32 v[158:159], v[158:159], v[182:183]
	v_mov_b32_e32 v202, v0
	v_mov_b32_e32 v204, v1
	v_mov_b32_e32 v206, v2
	v_mov_b32_e32 v208, v3
	v_pk_add_f32 v[156:157], v[156:157], v[158:159]
	v_pk_add_f32 v[158:159], v[202:203], v[204:205]
	v_pk_add_f32 v[182:183], v[206:207], v[208:209]
	s_nop 0
	v_pk_add_f32 v[158:159], v[158:159], v[182:183]
	s_nop 0
	v_pk_add_f32 v[156:157], v[156:157], v[158:159]
	v_mov_b32_e32 v158, v156
	v_mov_b32_e32 v159, v157
	s_nop 1
	v_permlane16_swap_b32_e32 v156, v158
	v_permlane16_swap_b32_e32 v157, v159
	v_pk_add_f32 v[156:157], v[156:157], v[158:159]
	v_mov_b32_e32 v158, v156
	v_mov_b32_e32 v159, v157
	s_nop 1
	v_permlane32_swap_b32_e32 v156, v158
	v_permlane32_swap_b32_e32 v157, v159
	s_and_saveexec_b64 s[38:39], s[36:37]
	s_cbranch_execz .LBB0_493
	v_pk_add_f32 v[156:157], v[156:157], v[158:159]
	ds_write_b64 v180, v[156:157] offset:5632
